# branch-merge phase rewritten by hand with a 3-stage LDS ring (two K chunks in flight), same arithmetic order
# speedup vs baseline: 1.0313x; 1.0132x over previous
; #define LAS __attribute__((address_space(3)))
; __device__ __forceinline__ int ltid(int wv) { unsigned z = 0u; asm volatile("" : "+v"(z)); return wv * 64 + (int)__builtin_amdgcn_mbcnt_hi(~0u, __builtin_amdgcn_mbcnt_lo(~0u, z)); }
; __device__ __forceinline__ int lgrid() { int g = gridDim.x; asm volatile("" : "+s"(g)); return g; }
; __device__ __forceinline__ int lbid() { int b = blockIdx.x; asm volatile("" : "+s"(b)); return b; }
; __device__ __forceinline__ void branch_phase(LAS unsigned char* lds, const bf16_t* __restrict__ O, const bf16_t* __restrict__ Wb, const bf16_t* __restrict__ Gt, bf16_t* __restrict__ MG, int tg, int wv) {
;     const int tid = ltid(wv), lane = tid & 63, wave = tid >> 6, wm = wave >> 2, wn = wave & 3, fr = lane & 15, fq = lane >> 4;
;     const int G_ = lgrid(), b_ = lbid(), vb = (G_ % 8 == 0) ? (b_ % 8) * (G_ / 8) + b_ / 8 : b_;
;     const int ntile = (tg / 128) * 4;
;     constexpr int STG = 49152;
;     int pR[2], pC[2];
; #pragma unroll
;     for (int i = 0; i < 2; ++i) pg8::stage_rc(tid * 16 + i * 8192, pR[i], pC[i]);
;     const int aoff = pg8::lds_byte(wm * 64 + fr, fq * 8), boff = 16384 + (wn >> 1) * 16384 + pg8::lds_byte((wn & 1) * 64 + fr, fq * 8);
;     __syncthreads();
;     for (int tile = vb; tile < ntile; tile += G_) {
;         const int rt = tile >> 2, ct = tile & 3;
;         const bf16_t* Ab = O + (size_t)(rt * 128) * 1024;
;         u32x2 sum[4][4];
; #pragma unroll
;         for (int m = 0; m < 4; ++m)
; #pragma unroll
;             for (int n = 0; n < 4; ++n) sum[m][n] = (u32x2){0u, 0u};
;     ...
;         BR_LOAD(0, 0);
;         asm volatile("s_waitcnt vmcnt(0)" ::: "memory"); __syncthreads();
.LBB0_276:
	s_lshr_b32 s6, s51, 5
	s_cmp_ge_i32 s5, s6
	s_waitcnt vmcnt(0) lgkmcnt(0)
	s_barrier
	s_cbranch_scc1 .LBB0_283
	v_mbcnt_lo_u32_b32 v196, -1, 0
	v_mbcnt_hi_u32_b32 v196, -1, v196
	v_readlane_b32 s78, v255, 1
	s_nop 1
	s_lshr_b32 s9, s78, 6
	s_lshl_b32 s78, s78, 4
	v_lshlrev_b32_e32 v206, 4, v196
	v_and_b32_e32 v207, 32, v196
	v_xor_b32_e32 v206, v206, v207
	v_lshrrev_b32_e32 v207, 6, v206
	s_lshr_b32 s10, s9, 1
	s_lshl_b32 s10, s10, 4
	v_add_u32_e32 v207, s10, v207
	v_and_b32_e32 v208, 63, v206
	v_lshrrev_b32_e32 v208, 1, v208
	s_and_b32 s10, s9, 1
	s_lshl_b32 s10, s10, 5
	v_add_u32_e32 v208, s10, v208
	v_lshlrev_b32_e32 v208, 1, v208
	v_lshl_add_u32 v197, v207, 11, v208
	v_add_u32_e32 v198, 0x20000, v197
	v_lshl_add_u32 v199, v207, 9, v208
	v_add_u32_e32 v200, 0x8000, v199
	v_and_b32_e32 v206, 15, v196
	v_lshrrev_b32_e32 v207, 4, v196
	v_lshlrev_b32_e32 v208, 6, v206
	v_lshl_add_u32 v208, v207, 4, v208
	v_lshlrev_b32_e32 v209, 2, v206
	v_and_b32_e32 v209, 32, v209
	v_xor_b32_e32 v208, v208, v209
	s_lshr_b32 s10, s9, 2
	s_lshl_b32 s11, s10, 13
	v_add_u32_e32 v201, s11, v208
	s_and_b32 s11, s9, 3
	s_and_b32 s12, s11, 1
	s_lshl_b32 s12, s12, 13
	s_lshr_b32 s13, s11, 1
	s_lshl_b32 s21, s13, 14
	s_add_i32 s12, s12, s21
	s_add_i32 s12, s12, 0x4000
	v_add_u32_e32 v202, s12, v208
	s_lshl_b32 s21, s13, 11
	v_add_u32_e32 v203, s21, v202
	v_add_u32_e32 v214, 0x0, v201
	v_add_u32_e32 v217, 0x0, v202
	v_add_u32_e32 v215, 0xc000, v201
	v_add_u32_e32 v218, 0xc000, v202
	v_add_u32_e32 v216, 0x18000, v201
	v_add_u32_e32 v219, 0x18000, v203
	s_lshl_b32 s12, s10, 6
	v_add_u32_e32 v210, s12, v206
	s_lshl_b32 s12, s11, 7
	v_lshl_add_u32 v211, v207, 3, s12
	v_lshl_add_u32 v204, v210, 13, v211
	v_and_b32_e32 v211, 1, v207
	v_lshlrev_b32_e32 v211, 5, v211
	v_lshrrev_b32_e32 v212, 1, v207
	v_lshl_add_u32 v211, v212, 4, v211
	v_add_u32_e32 v211, s12, v211
	v_lshl_add_u32 v205, v210, 11, v211
.Lph6_tile:
	s_lshr_b32 s9, s5, 2
	s_and_b32 s10, s5, 3
	s_lshl_b32 s11, s9, 18
	s_add_u32 s64, s18, s11
	s_addc_u32 s65, s19, 0
	s_add_u32 s64, s64, 0x1e200000
	s_addc_u32 s65, s65, 0
	s_lshl_b32 s11, s10, 17
	s_add_u32 s68, s57, s11
	s_addc_u32 s69, s58, 0
	s_add_u32 s68, s68, 0x1100000
	s_addc_u32 s69, s69, 0
	s_lshl_b32 s11, s9, 20
	s_lshl_b32 s12, s10, 9
	s_add_u32 s74, s18, s11
	s_addc_u32 s75, s19, 0
	s_add_u32 s74, s74, s12
	s_addc_u32 s75, s75, 0
	s_add_u32 s74, s74, 0xa200000
	s_addc_u32 s75, s75, 0
	s_lshl_b32 s11, s9, 18
	s_add_u32 s76, s18, s11
	s_addc_u32 s77, s19, 0
	s_add_u32 s76, s76, s12
	s_addc_u32 s77, s77, 0
	s_add_u32 s76, s76, 0x29400000
	s_addc_u32 s77, s77, 0
	v_mov_b32_e32 v66, 0
	v_mov_b32_e32 v67, 0
	v_mov_b32_e32 v68, 0
	v_mov_b32_e32 v69, 0
	v_mov_b32_e32 v70, 0
	v_mov_b32_e32 v71, 0
	v_mov_b32_e32 v72, 0
	v_mov_b32_e32 v73, 0
	v_mov_b32_e32 v74, 0
	v_mov_b32_e32 v75, 0
	v_mov_b32_e32 v76, 0
	v_mov_b32_e32 v77, 0
	v_mov_b32_e32 v78, 0
	v_mov_b32_e32 v79, 0
	v_mov_b32_e32 v80, 0
	v_mov_b32_e32 v81, 0
	v_mov_b32_e32 v82, 0
	v_mov_b32_e32 v83, 0
	v_mov_b32_e32 v84, 0
	v_mov_b32_e32 v85, 0
	v_mov_b32_e32 v86, 0
	v_mov_b32_e32 v87, 0
	v_mov_b32_e32 v88, 0
	v_mov_b32_e32 v89, 0
	v_mov_b32_e32 v90, 0
	v_mov_b32_e32 v91, 0
	v_mov_b32_e32 v92, 0
	v_mov_b32_e32 v93, 0
	v_mov_b32_e32 v94, 0
	v_mov_b32_e32 v95, 0
	v_mov_b32_e32 v96, 0
	v_mov_b32_e32 v97, 0
	s_waitcnt lgkmcnt(0)
	s_barrier
	s_add_u32 s66, s64, 0x0
	s_addc_u32 s67, s65, 0
	s_add_u32 s70, s68, 0x0
	s_addc_u32 s71, s69, 0
	s_add_u32 s72, s70, 0x10000
	s_addc_u32 s73, s71, 0
	s_add_i32 m0, s78, 0x0
	s_nop 0
	global_load_lds_dwordx4 v197, s[66:67]
	s_add_i32 m0, s78, 0x2000
	s_nop 0
	global_load_lds_dwordx4 v198, s[66:67]
	s_add_i32 m0, s78, 0x4000
	s_nop 0
	global_load_lds_dwordx4 v199, s[70:71]
	s_add_i32 m0, s78, 0x6000
	s_nop 0
	global_load_lds_dwordx4 v200, s[70:71]
	s_add_i32 m0, s78, 0x8000
	s_nop 0
	global_load_lds_dwordx4 v199, s[72:73]
	s_add_i32 m0, s78, 0xa000
	s_nop 0
	global_load_lds_dwordx4 v200, s[72:73]
	s_add_u32 s66, s64, 0x80
	s_addc_u32 s67, s65, 0
	s_add_u32 s70, s68, 0x80
	s_addc_u32 s71, s69, 0
	s_add_u32 s72, s70, 0x10000
	s_addc_u32 s73, s71, 0
	s_add_i32 m0, s78, 0xc000
	s_nop 0
	global_load_lds_dwordx4 v197, s[66:67]
	s_add_i32 m0, s78, 0xe000
	s_nop 0
	global_load_lds_dwordx4 v198, s[66:67]
	s_add_i32 m0, s78, 0x10000
	s_nop 0
	global_load_lds_dwordx4 v199, s[70:71]
	s_add_i32 m0, s78, 0x12000
	s_nop 0
	global_load_lds_dwordx4 v200, s[70:71]
	s_add_i32 m0, s78, 0x14000
	s_nop 0
	global_load_lds_dwordx4 v199, s[72:73]
	s_add_i32 m0, s78, 0x16000
	s_nop 0
	global_load_lds_dwordx4 v200, s[72:73]
	s_waitcnt vmcnt(6)
	s_barrier
; #define LAS __attribute__((address_space(3)))
; __device__ __forceinline__ void branch_phase(LAS unsigned char* lds, const bf16_t* __restrict__ O, const bf16_t* __restrict__ Wb, const bf16_t* __restrict__ Gt, bf16_t* __restrict__ MG, int tg, int wv) {
;     ...
;         for (int j = 0; j < 4; ++j) {
;             u32x2 gv[4][4];
;             f32x4 acc[4][4];
; #pragma unroll
;             for (int m = 0; m < 4; ++m)
; #pragma unroll
;                 for (int n = 0; n < 4; ++n) acc[m][n] = (f32x4){0.f, 0.f, 0.f, 0.f};
;             for (int kc = 0; kc < 4; ++kc) {
;                 const int c = j * 4 + kc;
;                 if (c + 1 < 16) BR_LOAD(c + 1, (c + 1) & 1);
;                 if (kc == 3) {
;                     const bf16_t* gp = Gt + (size_t)(rt * 128 + wm * 64 + fr) * ZC + j * 1024 + ct * 256 + wn * 64 + 4 * fq;
; #pragma unroll
;                     for (int m = 0; m < 4; ++m)
; #pragma unroll
;                         for (int n = 0; n < 4; ++n) gv[m][n] = *(const u32x2*)(gp + (size_t)m * 16 * ZC + n * 16);
;                 }
;                 LAS const unsigned char* st = lds + (c & 1) * STG;
; #pragma unroll
;                 for (int k = 0; k < 2; ++k) {
;                     __builtin_amdgcn_sched_barrier(0);
;                     bf16x8 af[4], bfr[4];
; #pragma unroll
;                     for (int m = 0; m < 4; ++m) af[m] = *(LAS const bf16x8*)(st + aoff + m * 2048 + k * 1024);
; #pragma unroll
;                     for (int n = 0; n < 4; ++n) bfr[n] = *(LAS const bf16x8*)(st + boff + n * 2048 + k * 1024);
; #pragma unroll
;                     for (int m = 0; m < 4; ++m)
; #pragma unroll
;                         for (int n = 0; n < 4; ++n) acc[m][n] = __builtin_amdgcn_mfma_f32_16x16x32_bf16(bfr[n], af[m], acc[m][n], 0, 0, 0);
;                 }
;                 asm volatile("s_waitcnt vmcnt(0)" ::: "memory"); __syncthreads();
	s_add_u32 s66, s64, 0x100
	s_addc_u32 s67, s65, 0
	s_add_u32 s70, s68, 0x100
	s_addc_u32 s71, s69, 0
	s_add_u32 s72, s70, 0x10000
	s_addc_u32 s73, s71, 0
	s_add_i32 m0, s78, 0x18000
	s_nop 0
	global_load_lds_dwordx4 v197, s[66:67]
	s_add_i32 m0, s78, 0x1a000
	s_nop 0
	global_load_lds_dwordx4 v198, s[66:67]
	s_add_i32 m0, s78, 0x1c000
	s_nop 0
	global_load_lds_dwordx4 v199, s[70:71]
	s_add_i32 m0, s78, 0x1e000
	s_nop 0
	global_load_lds_dwordx4 v200, s[70:71]
	s_add_i32 m0, s78, 0x20800
	s_nop 0
	global_load_lds_dwordx4 v199, s[72:73]
	s_add_i32 m0, s78, 0x22800
	s_nop 0
	global_load_lds_dwordx4 v200, s[72:73]
	ds_read_b128 v[130:133], v214 offset:0
	ds_read_b128 v[134:137], v214 offset:2048
	ds_read_b128 v[138:141], v214 offset:4096
	ds_read_b128 v[142:145], v214 offset:6144
	ds_read_b128 v[162:165], v217 offset:0
	ds_read_b128 v[166:169], v217 offset:2048
	ds_read_b128 v[170:173], v217 offset:4096
	ds_read_b128 v[174:177], v217 offset:6144
	ds_read_b128 v[146:149], v214 offset:1024
	ds_read_b128 v[150:153], v214 offset:3072
	ds_read_b128 v[154:157], v214 offset:5120
	ds_read_b128 v[158:161], v214 offset:7168
	ds_read_b128 v[178:181], v217 offset:1024
	ds_read_b128 v[182:185], v217 offset:3072
	ds_read_b128 v[186:189], v217 offset:5120
	ds_read_b128 v[190:193], v217 offset:7168
	s_waitcnt lgkmcnt(8)
	v_mfma_f32_16x16x32_bf16 v[2:5], v[162:165], v[130:133], 0
	v_mfma_f32_16x16x32_bf16 v[6:9], v[166:169], v[130:133], 0
	v_mfma_f32_16x16x32_bf16 v[10:13], v[170:173], v[130:133], 0
	v_mfma_f32_16x16x32_bf16 v[14:17], v[174:177], v[130:133], 0
	v_mfma_f32_16x16x32_bf16 v[18:21], v[162:165], v[134:137], 0
	v_mfma_f32_16x16x32_bf16 v[22:25], v[166:169], v[134:137], 0
	v_mfma_f32_16x16x32_bf16 v[26:29], v[170:173], v[134:137], 0
	v_mfma_f32_16x16x32_bf16 v[30:33], v[174:177], v[134:137], 0
	v_mfma_f32_16x16x32_bf16 v[34:37], v[162:165], v[138:141], 0
	v_mfma_f32_16x16x32_bf16 v[38:41], v[166:169], v[138:141], 0
	v_mfma_f32_16x16x32_bf16 v[42:45], v[170:173], v[138:141], 0
	v_mfma_f32_16x16x32_bf16 v[46:49], v[174:177], v[138:141], 0
	v_mfma_f32_16x16x32_bf16 v[50:53], v[162:165], v[142:145], 0
	v_mfma_f32_16x16x32_bf16 v[54:57], v[166:169], v[142:145], 0
	v_mfma_f32_16x16x32_bf16 v[58:61], v[170:173], v[142:145], 0
	v_mfma_f32_16x16x32_bf16 v[62:65], v[174:177], v[142:145], 0
	s_waitcnt lgkmcnt(0)
	v_mfma_f32_16x16x32_bf16 v[2:5], v[178:181], v[146:149], v[2:5]
	v_mfma_f32_16x16x32_bf16 v[6:9], v[182:185], v[146:149], v[6:9]
	v_mfma_f32_16x16x32_bf16 v[10:13], v[186:189], v[146:149], v[10:13]
	v_mfma_f32_16x16x32_bf16 v[14:17], v[190:193], v[146:149], v[14:17]
	v_mfma_f32_16x16x32_bf16 v[18:21], v[178:181], v[150:153], v[18:21]
	v_mfma_f32_16x16x32_bf16 v[22:25], v[182:185], v[150:153], v[22:25]
	v_mfma_f32_16x16x32_bf16 v[26:29], v[186:189], v[150:153], v[26:29]
	v_mfma_f32_16x16x32_bf16 v[30:33], v[190:193], v[150:153], v[30:33]
	v_mfma_f32_16x16x32_bf16 v[34:37], v[178:181], v[154:157], v[34:37]
	v_mfma_f32_16x16x32_bf16 v[38:41], v[182:185], v[154:157], v[38:41]
	v_mfma_f32_16x16x32_bf16 v[42:45], v[186:189], v[154:157], v[42:45]
	v_mfma_f32_16x16x32_bf16 v[46:49], v[190:193], v[154:157], v[46:49]
	v_mfma_f32_16x16x32_bf16 v[50:53], v[178:181], v[158:161], v[50:53]
	v_mfma_f32_16x16x32_bf16 v[54:57], v[182:185], v[158:161], v[54:57]
	v_mfma_f32_16x16x32_bf16 v[58:61], v[186:189], v[158:161], v[58:61]
	v_mfma_f32_16x16x32_bf16 v[62:65], v[190:193], v[158:161], v[62:65]
	s_waitcnt vmcnt(6)
	s_barrier
	s_add_u32 s66, s64, 0x180
	s_addc_u32 s67, s65, 0
	s_add_u32 s70, s68, 0x180
	s_addc_u32 s71, s69, 0
	s_add_u32 s72, s70, 0x10000
	s_addc_u32 s73, s71, 0
	s_add_i32 m0, s78, 0x0
	s_nop 0
	global_load_lds_dwordx4 v197, s[66:67]
	s_add_i32 m0, s78, 0x2000
	s_nop 0
	global_load_lds_dwordx4 v198, s[66:67]
	s_add_i32 m0, s78, 0x4000
	s_nop 0
	global_load_lds_dwordx4 v199, s[70:71]
	s_add_i32 m0, s78, 0x6000
	s_nop 0
	global_load_lds_dwordx4 v200, s[70:71]
	s_add_i32 m0, s78, 0x8000
	s_nop 0
	global_load_lds_dwordx4 v199, s[72:73]
	s_add_i32 m0, s78, 0xa000
	s_nop 0
	global_load_lds_dwordx4 v200, s[72:73]
	s_add_u32 s80, s74, 0x0
	s_addc_u32 s81, s75, 0
	global_load_dwordx2 v[98:99], v204, s[80:81] offset:0
	global_load_dwordx2 v[100:101], v204, s[80:81] offset:32
	global_load_dwordx2 v[102:103], v204, s[80:81] offset:64
	global_load_dwordx2 v[104:105], v204, s[80:81] offset:96
	s_add_u32 s80, s80, 0x20000
	s_addc_u32 s81, s81, 0
	global_load_dwordx2 v[106:107], v204, s[80:81] offset:0
	global_load_dwordx2 v[108:109], v204, s[80:81] offset:32
	global_load_dwordx2 v[110:111], v204, s[80:81] offset:64
	global_load_dwordx2 v[112:113], v204, s[80:81] offset:96
	s_add_u32 s80, s80, 0x20000
	s_addc_u32 s81, s81, 0
	global_load_dwordx2 v[114:115], v204, s[80:81] offset:0
	global_load_dwordx2 v[116:117], v204, s[80:81] offset:32
	global_load_dwordx2 v[118:119], v204, s[80:81] offset:64
	global_load_dwordx2 v[120:121], v204, s[80:81] offset:96
	s_add_u32 s80, s80, 0x20000
	s_addc_u32 s81, s81, 0
	global_load_dwordx2 v[122:123], v204, s[80:81] offset:0
	global_load_dwordx2 v[124:125], v204, s[80:81] offset:32
	global_load_dwordx2 v[126:127], v204, s[80:81] offset:64
	global_load_dwordx2 v[128:129], v204, s[80:81] offset:96
	ds_read_b128 v[130:133], v215 offset:0
	ds_read_b128 v[134:137], v215 offset:2048
	ds_read_b128 v[138:141], v215 offset:4096
	ds_read_b128 v[142:145], v215 offset:6144
	ds_read_b128 v[162:165], v218 offset:0
	ds_read_b128 v[166:169], v218 offset:2048
	ds_read_b128 v[170:173], v218 offset:4096
	ds_read_b128 v[174:177], v218 offset:6144
	ds_read_b128 v[146:149], v215 offset:1024
	ds_read_b128 v[150:153], v215 offset:3072
	ds_read_b128 v[154:157], v215 offset:5120
	ds_read_b128 v[158:161], v215 offset:7168
	ds_read_b128 v[178:181], v218 offset:1024
	ds_read_b128 v[182:185], v218 offset:3072
	ds_read_b128 v[186:189], v218 offset:5120
	ds_read_b128 v[190:193], v218 offset:7168
	s_waitcnt lgkmcnt(8)
; #define LAS __attribute__((address_space(3)))
; __device__ __forceinline__ void branch_phase(LAS unsigned char* lds, const bf16_t* __restrict__ O, const bf16_t* __restrict__ Wb, const bf16_t* __restrict__ Gt, bf16_t* __restrict__ MG, int tg, int wv) {
;     ...
;             for (int kc = 0; kc < 4; ++kc) {
;                 const int c = j * 4 + kc;
;                 if (c + 1 < 16) BR_LOAD(c + 1, (c + 1) & 1);
;                 if (kc == 3) {
;                     const bf16_t* gp = Gt + (size_t)(rt * 128 + wm * 64 + fr) * ZC + j * 1024 + ct * 256 + wn * 64 + 4 * fq;
; #pragma unroll
;                     for (int m = 0; m < 4; ++m)
; #pragma unroll
;                         for (int n = 0; n < 4; ++n) gv[m][n] = *(const u32x2*)(gp + (size_t)m * 16 * ZC + n * 16);
;                 }
;                 LAS const unsigned char* st = lds + (c & 1) * STG;
; #pragma unroll
;                 for (int k = 0; k < 2; ++k) {
;                     __builtin_amdgcn_sched_barrier(0);
;                     bf16x8 af[4], bfr[4];
; #pragma unroll
;                     for (int m = 0; m < 4; ++m) af[m] = *(LAS const bf16x8*)(st + aoff + m * 2048 + k * 1024);
; #pragma unroll
;                     for (int n = 0; n < 4; ++n) bfr[n] = *(LAS const bf16x8*)(st + boff + n * 2048 + k * 1024);
; #pragma unroll
;                     for (int m = 0; m < 4; ++m)
; #pragma unroll
;                         for (int n = 0; n < 4; ++n) acc[m][n] = __builtin_amdgcn_mfma_f32_16x16x32_bf16(bfr[n], af[m], acc[m][n], 0, 0, 0);
;                 }
;                 asm volatile("s_waitcnt vmcnt(0)" ::: "memory"); __syncthreads();
	v_mfma_f32_16x16x32_bf16 v[2:5], v[162:165], v[130:133], v[2:5]
	v_mfma_f32_16x16x32_bf16 v[6:9], v[166:169], v[130:133], v[6:9]
	v_mfma_f32_16x16x32_bf16 v[10:13], v[170:173], v[130:133], v[10:13]
	v_mfma_f32_16x16x32_bf16 v[14:17], v[174:177], v[130:133], v[14:17]
	v_mfma_f32_16x16x32_bf16 v[18:21], v[162:165], v[134:137], v[18:21]
	v_mfma_f32_16x16x32_bf16 v[22:25], v[166:169], v[134:137], v[22:25]
	v_mfma_f32_16x16x32_bf16 v[26:29], v[170:173], v[134:137], v[26:29]
	v_mfma_f32_16x16x32_bf16 v[30:33], v[174:177], v[134:137], v[30:33]
	v_mfma_f32_16x16x32_bf16 v[34:37], v[162:165], v[138:141], v[34:37]
	v_mfma_f32_16x16x32_bf16 v[38:41], v[166:169], v[138:141], v[38:41]
	v_mfma_f32_16x16x32_bf16 v[42:45], v[170:173], v[138:141], v[42:45]
	v_mfma_f32_16x16x32_bf16 v[46:49], v[174:177], v[138:141], v[46:49]
	v_mfma_f32_16x16x32_bf16 v[50:53], v[162:165], v[142:145], v[50:53]
	v_mfma_f32_16x16x32_bf16 v[54:57], v[166:169], v[142:145], v[54:57]
	v_mfma_f32_16x16x32_bf16 v[58:61], v[170:173], v[142:145], v[58:61]
	v_mfma_f32_16x16x32_bf16 v[62:65], v[174:177], v[142:145], v[62:65]
	s_waitcnt lgkmcnt(0)
	v_mfma_f32_16x16x32_bf16 v[2:5], v[178:181], v[146:149], v[2:5]
	v_mfma_f32_16x16x32_bf16 v[6:9], v[182:185], v[146:149], v[6:9]
	v_mfma_f32_16x16x32_bf16 v[10:13], v[186:189], v[146:149], v[10:13]
	v_mfma_f32_16x16x32_bf16 v[14:17], v[190:193], v[146:149], v[14:17]
	v_mfma_f32_16x16x32_bf16 v[18:21], v[178:181], v[150:153], v[18:21]
	v_mfma_f32_16x16x32_bf16 v[22:25], v[182:185], v[150:153], v[22:25]
	v_mfma_f32_16x16x32_bf16 v[26:29], v[186:189], v[150:153], v[26:29]
	v_mfma_f32_16x16x32_bf16 v[30:33], v[190:193], v[150:153], v[30:33]
	v_mfma_f32_16x16x32_bf16 v[34:37], v[178:181], v[154:157], v[34:37]
	v_mfma_f32_16x16x32_bf16 v[38:41], v[182:185], v[154:157], v[38:41]
	v_mfma_f32_16x16x32_bf16 v[42:45], v[186:189], v[154:157], v[42:45]
	v_mfma_f32_16x16x32_bf16 v[46:49], v[190:193], v[154:157], v[46:49]
	v_mfma_f32_16x16x32_bf16 v[50:53], v[178:181], v[158:161], v[50:53]
	v_mfma_f32_16x16x32_bf16 v[54:57], v[182:185], v[158:161], v[54:57]
	v_mfma_f32_16x16x32_bf16 v[58:61], v[186:189], v[158:161], v[58:61]
	v_mfma_f32_16x16x32_bf16 v[62:65], v[190:193], v[158:161], v[62:65]
	s_waitcnt vmcnt(22)
	s_barrier
	s_add_u32 s66, s64, 0x200
	s_addc_u32 s67, s65, 0
	s_add_u32 s70, s68, 0x80000
	s_addc_u32 s71, s69, 0
	s_add_u32 s72, s70, 0x10000
	s_addc_u32 s73, s71, 0
	s_add_i32 m0, s78, 0xc000
	s_nop 0
	global_load_lds_dwordx4 v197, s[66:67]
	s_add_i32 m0, s78, 0xe000
	s_nop 0
	global_load_lds_dwordx4 v198, s[66:67]
	s_add_i32 m0, s78, 0x10000
	s_nop 0
	global_load_lds_dwordx4 v199, s[70:71]
	s_add_i32 m0, s78, 0x12000
	s_nop 0
	global_load_lds_dwordx4 v200, s[70:71]
	s_add_i32 m0, s78, 0x14000
	s_nop 0
	global_load_lds_dwordx4 v199, s[72:73]
	s_add_i32 m0, s78, 0x16000
	s_nop 0
	global_load_lds_dwordx4 v200, s[72:73]
	ds_read_b128 v[130:133], v216 offset:0
	ds_read_b128 v[134:137], v216 offset:2048
	ds_read_b128 v[138:141], v216 offset:4096
	ds_read_b128 v[142:145], v216 offset:6144
	ds_read_b128 v[162:165], v219 offset:0
	ds_read_b128 v[166:169], v219 offset:2048
	ds_read_b128 v[170:173], v219 offset:4096
	ds_read_b128 v[174:177], v219 offset:6144
	ds_read_b128 v[146:149], v216 offset:1024
	ds_read_b128 v[150:153], v216 offset:3072
	ds_read_b128 v[154:157], v216 offset:5120
	ds_read_b128 v[158:161], v216 offset:7168
	ds_read_b128 v[178:181], v219 offset:1024
	ds_read_b128 v[182:185], v219 offset:3072
	ds_read_b128 v[186:189], v219 offset:5120
	ds_read_b128 v[190:193], v219 offset:7168
	s_waitcnt lgkmcnt(8)
	v_mfma_f32_16x16x32_bf16 v[2:5], v[162:165], v[130:133], v[2:5]
	v_mfma_f32_16x16x32_bf16 v[6:9], v[166:169], v[130:133], v[6:9]
	v_mfma_f32_16x16x32_bf16 v[10:13], v[170:173], v[130:133], v[10:13]
	v_mfma_f32_16x16x32_bf16 v[14:17], v[174:177], v[130:133], v[14:17]
	v_mfma_f32_16x16x32_bf16 v[18:21], v[162:165], v[134:137], v[18:21]
	v_mfma_f32_16x16x32_bf16 v[22:25], v[166:169], v[134:137], v[22:25]
	v_mfma_f32_16x16x32_bf16 v[26:29], v[170:173], v[134:137], v[26:29]
	v_mfma_f32_16x16x32_bf16 v[30:33], v[174:177], v[134:137], v[30:33]
	v_mfma_f32_16x16x32_bf16 v[34:37], v[162:165], v[138:141], v[34:37]
	v_mfma_f32_16x16x32_bf16 v[38:41], v[166:169], v[138:141], v[38:41]
	v_mfma_f32_16x16x32_bf16 v[42:45], v[170:173], v[138:141], v[42:45]
	v_mfma_f32_16x16x32_bf16 v[46:49], v[174:177], v[138:141], v[46:49]
	v_mfma_f32_16x16x32_bf16 v[50:53], v[162:165], v[142:145], v[50:53]
	v_mfma_f32_16x16x32_bf16 v[54:57], v[166:169], v[142:145], v[54:57]
	v_mfma_f32_16x16x32_bf16 v[58:61], v[170:173], v[142:145], v[58:61]
	v_mfma_f32_16x16x32_bf16 v[62:65], v[174:177], v[142:145], v[62:65]
	s_waitcnt lgkmcnt(0)
	v_mfma_f32_16x16x32_bf16 v[2:5], v[178:181], v[146:149], v[2:5]
	v_mfma_f32_16x16x32_bf16 v[6:9], v[182:185], v[146:149], v[6:9]
	v_mfma_f32_16x16x32_bf16 v[10:13], v[186:189], v[146:149], v[10:13]
	v_mfma_f32_16x16x32_bf16 v[14:17], v[190:193], v[146:149], v[14:17]
	v_mfma_f32_16x16x32_bf16 v[18:21], v[178:181], v[150:153], v[18:21]
	v_mfma_f32_16x16x32_bf16 v[22:25], v[182:185], v[150:153], v[22:25]
	v_mfma_f32_16x16x32_bf16 v[26:29], v[186:189], v[150:153], v[26:29]
	v_mfma_f32_16x16x32_bf16 v[30:33], v[190:193], v[150:153], v[30:33]
	v_mfma_f32_16x16x32_bf16 v[34:37], v[178:181], v[154:157], v[34:37]
	v_mfma_f32_16x16x32_bf16 v[38:41], v[182:185], v[154:157], v[38:41]
	v_mfma_f32_16x16x32_bf16 v[42:45], v[186:189], v[154:157], v[42:45]
	v_mfma_f32_16x16x32_bf16 v[46:49], v[190:193], v[154:157], v[46:49]
	v_mfma_f32_16x16x32_bf16 v[50:53], v[178:181], v[158:161], v[50:53]
	v_mfma_f32_16x16x32_bf16 v[54:57], v[182:185], v[158:161], v[54:57]
	v_mfma_f32_16x16x32_bf16 v[58:61], v[186:189], v[158:161], v[58:61]
	v_mfma_f32_16x16x32_bf16 v[62:65], v[190:193], v[158:161], v[62:65]
	s_waitcnt vmcnt(22)
	s_barrier
; #define LAS __attribute__((address_space(3)))
; __device__ __forceinline__ unsigned cvtpk(float lo, float hi) { f32x2 v = {lo, hi}; bf16x2_t b = __builtin_convertvector(v, bf16x2_t); return __builtin_bit_cast(unsigned, b); }
; __device__ __forceinline__ void branch_phase(LAS unsigned char* lds, const bf16_t* __restrict__ O, const bf16_t* __restrict__ Wb, const bf16_t* __restrict__ Gt, bf16_t* __restrict__ MG, int tg, int wv) {
;     ...
;                     for (int m = 0; m < 4; ++m) af[m] = *(LAS const bf16x8*)(st + aoff + m * 2048 + k * 1024);
; #pragma unroll
;                     for (int n = 0; n < 4; ++n) bfr[n] = *(LAS const bf16x8*)(st + boff + n * 2048 + k * 1024);
; #pragma unroll
;                     for (int m = 0; m < 4; ++m)
; #pragma unroll
;                         for (int n = 0; n < 4; ++n) acc[m][n] = __builtin_amdgcn_mfma_f32_16x16x32_bf16(bfr[n], af[m], acc[m][n], 0, 0, 0);
;                 }
;                 asm volatile("s_waitcnt vmcnt(0)" ::: "memory"); __syncthreads();
;             }
; #pragma unroll
;             for (int m = 0; m < 4; ++m)
; #pragma unroll
;                 for (int n = 0; n < 4; ++n) { const u32x2 g = gv[m][n], sp = sum[m][n];
;                     const float s0_ = __builtin_bit_cast(float, sp.x << 16) + acc[m][n][0] * __builtin_bit_cast(float, g.x << 16), s1_ = __builtin_bit_cast(float, sp.x & 0xffff0000u) + acc[m][n][1] * __builtin_bit_cast(float, g.x & 0xffff0000u);
;                     const float s2_ = __builtin_bit_cast(float, sp.y << 16) + acc[m][n][2] * __builtin_bit_cast(float, g.y << 16), s3_ = __builtin_bit_cast(float, sp.y & 0xffff0000u) + acc[m][n][3] * __builtin_bit_cast(float, g.y & 0xffff0000u);
;                     sum[m][n] = (u32x2){cvtpk(s0_, s1_), cvtpk(s2_, s3_)}; }
	s_add_u32 s66, s64, 0x280
	s_addc_u32 s67, s65, 0
	s_add_u32 s70, s68, 0x80080
	s_addc_u32 s71, s69, 0
	s_add_u32 s72, s70, 0x10000
	s_addc_u32 s73, s71, 0
	s_add_i32 m0, s78, 0x18000
	s_nop 0
	global_load_lds_dwordx4 v197, s[66:67]
	s_add_i32 m0, s78, 0x1a000
	s_nop 0
	global_load_lds_dwordx4 v198, s[66:67]
	s_add_i32 m0, s78, 0x1c000
	s_nop 0
	global_load_lds_dwordx4 v199, s[70:71]
	s_add_i32 m0, s78, 0x1e000
	s_nop 0
	global_load_lds_dwordx4 v200, s[70:71]
	s_add_i32 m0, s78, 0x20800
	s_nop 0
	global_load_lds_dwordx4 v199, s[72:73]
	s_add_i32 m0, s78, 0x22800
	s_nop 0
	global_load_lds_dwordx4 v200, s[72:73]
	ds_read_b128 v[130:133], v214 offset:0
	ds_read_b128 v[134:137], v214 offset:2048
	ds_read_b128 v[138:141], v214 offset:4096
	ds_read_b128 v[142:145], v214 offset:6144
	ds_read_b128 v[162:165], v217 offset:0
	ds_read_b128 v[166:169], v217 offset:2048
	ds_read_b128 v[170:173], v217 offset:4096
	ds_read_b128 v[174:177], v217 offset:6144
	ds_read_b128 v[146:149], v214 offset:1024
	ds_read_b128 v[150:153], v214 offset:3072
	ds_read_b128 v[154:157], v214 offset:5120
	ds_read_b128 v[158:161], v214 offset:7168
	ds_read_b128 v[178:181], v217 offset:1024
	ds_read_b128 v[182:185], v217 offset:3072
	ds_read_b128 v[186:189], v217 offset:5120
	ds_read_b128 v[190:193], v217 offset:7168
	s_waitcnt lgkmcnt(8)
	v_mfma_f32_16x16x32_bf16 v[2:5], v[162:165], v[130:133], v[2:5]
	v_mfma_f32_16x16x32_bf16 v[6:9], v[166:169], v[130:133], v[6:9]
	v_mfma_f32_16x16x32_bf16 v[10:13], v[170:173], v[130:133], v[10:13]
	v_mfma_f32_16x16x32_bf16 v[14:17], v[174:177], v[130:133], v[14:17]
	v_mfma_f32_16x16x32_bf16 v[18:21], v[162:165], v[134:137], v[18:21]
	v_mfma_f32_16x16x32_bf16 v[22:25], v[166:169], v[134:137], v[22:25]
	v_mfma_f32_16x16x32_bf16 v[26:29], v[170:173], v[134:137], v[26:29]
	v_mfma_f32_16x16x32_bf16 v[30:33], v[174:177], v[134:137], v[30:33]
	v_mfma_f32_16x16x32_bf16 v[34:37], v[162:165], v[138:141], v[34:37]
	v_mfma_f32_16x16x32_bf16 v[38:41], v[166:169], v[138:141], v[38:41]
	v_mfma_f32_16x16x32_bf16 v[42:45], v[170:173], v[138:141], v[42:45]
	v_mfma_f32_16x16x32_bf16 v[46:49], v[174:177], v[138:141], v[46:49]
	v_mfma_f32_16x16x32_bf16 v[50:53], v[162:165], v[142:145], v[50:53]
	v_mfma_f32_16x16x32_bf16 v[54:57], v[166:169], v[142:145], v[54:57]
	v_mfma_f32_16x16x32_bf16 v[58:61], v[170:173], v[142:145], v[58:61]
	v_mfma_f32_16x16x32_bf16 v[62:65], v[174:177], v[142:145], v[62:65]
	s_waitcnt lgkmcnt(0)
	v_mfma_f32_16x16x32_bf16 v[2:5], v[178:181], v[146:149], v[2:5]
	v_mfma_f32_16x16x32_bf16 v[6:9], v[182:185], v[146:149], v[6:9]
	v_mfma_f32_16x16x32_bf16 v[10:13], v[186:189], v[146:149], v[10:13]
	v_mfma_f32_16x16x32_bf16 v[14:17], v[190:193], v[146:149], v[14:17]
	v_mfma_f32_16x16x32_bf16 v[18:21], v[178:181], v[150:153], v[18:21]
	v_mfma_f32_16x16x32_bf16 v[22:25], v[182:185], v[150:153], v[22:25]
	v_mfma_f32_16x16x32_bf16 v[26:29], v[186:189], v[150:153], v[26:29]
	v_mfma_f32_16x16x32_bf16 v[30:33], v[190:193], v[150:153], v[30:33]
	v_mfma_f32_16x16x32_bf16 v[34:37], v[178:181], v[154:157], v[34:37]
	v_mfma_f32_16x16x32_bf16 v[38:41], v[182:185], v[154:157], v[38:41]
	v_mfma_f32_16x16x32_bf16 v[42:45], v[186:189], v[154:157], v[42:45]
	v_mfma_f32_16x16x32_bf16 v[46:49], v[190:193], v[154:157], v[46:49]
	v_mfma_f32_16x16x32_bf16 v[50:53], v[178:181], v[158:161], v[50:53]
	v_mfma_f32_16x16x32_bf16 v[54:57], v[182:185], v[158:161], v[54:57]
	v_mfma_f32_16x16x32_bf16 v[58:61], v[186:189], v[158:161], v[58:61]
	v_mfma_f32_16x16x32_bf16 v[62:65], v[190:193], v[158:161], v[62:65]
	s_waitcnt vmcnt(6)
	s_barrier
	s_nop 7
	v_lshlrev_b32_e32 v206, 16, v98
	v_and_b32_e32 v207, 0xffff0000, v98
	v_lshlrev_b32_e32 v208, 16, v99
	v_and_b32_e32 v209, 0xffff0000, v99
	v_lshlrev_b32_e32 v210, 16, v66
	v_and_b32_e32 v211, 0xffff0000, v66
	v_lshlrev_b32_e32 v212, 16, v67
	v_and_b32_e32 v213, 0xffff0000, v67
	v_pk_fma_f32 v[210:211], v[2:3], v[206:207], v[210:211]
	v_pk_fma_f32 v[212:213], v[4:5], v[208:209], v[212:213]
	v_cvt_pk_bf16_f32 v66, v210, v211
	v_cvt_pk_bf16_f32 v67, v212, v213
	v_lshlrev_b32_e32 v206, 16, v100
	v_and_b32_e32 v207, 0xffff0000, v100
	v_lshlrev_b32_e32 v208, 16, v101
	v_and_b32_e32 v209, 0xffff0000, v101
	v_lshlrev_b32_e32 v210, 16, v68
	v_and_b32_e32 v211, 0xffff0000, v68
	v_lshlrev_b32_e32 v212, 16, v69
	v_and_b32_e32 v213, 0xffff0000, v69
	v_pk_fma_f32 v[210:211], v[6:7], v[206:207], v[210:211]
	v_pk_fma_f32 v[212:213], v[8:9], v[208:209], v[212:213]
	v_cvt_pk_bf16_f32 v68, v210, v211
	v_cvt_pk_bf16_f32 v69, v212, v213
	v_lshlrev_b32_e32 v206, 16, v102
	v_and_b32_e32 v207, 0xffff0000, v102
	v_lshlrev_b32_e32 v208, 16, v103
	v_and_b32_e32 v209, 0xffff0000, v103
	v_lshlrev_b32_e32 v210, 16, v70
	v_and_b32_e32 v211, 0xffff0000, v70
	v_lshlrev_b32_e32 v212, 16, v71
	v_and_b32_e32 v213, 0xffff0000, v71
	v_pk_fma_f32 v[210:211], v[10:11], v[206:207], v[210:211]
	v_pk_fma_f32 v[212:213], v[12:13], v[208:209], v[212:213]
	v_cvt_pk_bf16_f32 v70, v210, v211
	v_cvt_pk_bf16_f32 v71, v212, v213
	v_lshlrev_b32_e32 v206, 16, v104
	v_and_b32_e32 v207, 0xffff0000, v104
	v_lshlrev_b32_e32 v208, 16, v105
	v_and_b32_e32 v209, 0xffff0000, v105
	v_lshlrev_b32_e32 v210, 16, v72
	v_and_b32_e32 v211, 0xffff0000, v72
	v_lshlrev_b32_e32 v212, 16, v73
	v_and_b32_e32 v213, 0xffff0000, v73
	v_pk_fma_f32 v[210:211], v[14:15], v[206:207], v[210:211]
	v_pk_fma_f32 v[212:213], v[16:17], v[208:209], v[212:213]
	v_cvt_pk_bf16_f32 v72, v210, v211
	v_cvt_pk_bf16_f32 v73, v212, v213
	v_lshlrev_b32_e32 v206, 16, v106
	v_and_b32_e32 v207, 0xffff0000, v106
	v_lshlrev_b32_e32 v208, 16, v107
	v_and_b32_e32 v209, 0xffff0000, v107
	v_lshlrev_b32_e32 v210, 16, v74
; #define LAS __attribute__((address_space(3)))
; __device__ __forceinline__ unsigned cvtpk(float lo, float hi) { f32x2 v = {lo, hi}; bf16x2_t b = __builtin_convertvector(v, bf16x2_t); return __builtin_bit_cast(unsigned, b); }
; __device__ __forceinline__ void branch_phase(LAS unsigned char* lds, const bf16_t* __restrict__ O, const bf16_t* __restrict__ Wb, const bf16_t* __restrict__ Gt, bf16_t* __restrict__ MG, int tg, int wv) {
;     ...
;             for (int kc = 0; kc < 4; ++kc) {
;                 const int c = j * 4 + kc;
;                 if (c + 1 < 16) BR_LOAD(c + 1, (c + 1) & 1);
;                 if (kc == 3) {
;                     const bf16_t* gp = Gt + (size_t)(rt * 128 + wm * 64 + fr) * ZC + j * 1024 + ct * 256 + wn * 64 + 4 * fq;
; #pragma unroll
;                     for (int m = 0; m < 4; ++m)
; #pragma unroll
;                         for (int n = 0; n < 4; ++n) gv[m][n] = *(const u32x2*)(gp + (size_t)m * 16 * ZC + n * 16);
;                 }
;                 LAS const unsigned char* st = lds + (c & 1) * STG;
; #pragma unroll
;                 for (int k = 0; k < 2; ++k) {
;                     __builtin_amdgcn_sched_barrier(0);
;                     bf16x8 af[4], bfr[4];
; #pragma unroll
;                     for (int m = 0; m < 4; ++m) af[m] = *(LAS const bf16x8*)(st + aoff + m * 2048 + k * 1024);
; #pragma unroll
;                     for (int n = 0; n < 4; ++n) bfr[n] = *(LAS const bf16x8*)(st + boff + n * 2048 + k * 1024);
;     ...
; #pragma unroll
;             for (int m = 0; m < 4; ++m)
; #pragma unroll
;                 for (int n = 0; n < 4; ++n) { const u32x2 g = gv[m][n], sp = sum[m][n];
;                     const float s0_ = __builtin_bit_cast(float, sp.x << 16) + acc[m][n][0] * __builtin_bit_cast(float, g.x << 16), s1_ = __builtin_bit_cast(float, sp.x & 0xffff0000u) + acc[m][n][1] * __builtin_bit_cast(float, g.x & 0xffff0000u);
;                     const float s2_ = __builtin_bit_cast(float, sp.y << 16) + acc[m][n][2] * __builtin_bit_cast(float, g.y << 16), s3_ = __builtin_bit_cast(float, sp.y & 0xffff0000u) + acc[m][n][3] * __builtin_bit_cast(float, g.y & 0xffff0000u);
;                     sum[m][n] = (u32x2){cvtpk(s0_, s1_), cvtpk(s2_, s3_)}; }
	v_and_b32_e32 v211, 0xffff0000, v74
	v_lshlrev_b32_e32 v212, 16, v75
	v_and_b32_e32 v213, 0xffff0000, v75
	v_pk_fma_f32 v[210:211], v[18:19], v[206:207], v[210:211]
	v_pk_fma_f32 v[212:213], v[20:21], v[208:209], v[212:213]
	v_cvt_pk_bf16_f32 v74, v210, v211
	v_cvt_pk_bf16_f32 v75, v212, v213
	v_lshlrev_b32_e32 v206, 16, v108
	v_and_b32_e32 v207, 0xffff0000, v108
	v_lshlrev_b32_e32 v208, 16, v109
	v_and_b32_e32 v209, 0xffff0000, v109
	v_lshlrev_b32_e32 v210, 16, v76
	v_and_b32_e32 v211, 0xffff0000, v76
	v_lshlrev_b32_e32 v212, 16, v77
	v_and_b32_e32 v213, 0xffff0000, v77
	v_pk_fma_f32 v[210:211], v[22:23], v[206:207], v[210:211]
	v_pk_fma_f32 v[212:213], v[24:25], v[208:209], v[212:213]
	v_cvt_pk_bf16_f32 v76, v210, v211
	v_cvt_pk_bf16_f32 v77, v212, v213
	v_lshlrev_b32_e32 v206, 16, v110
	v_and_b32_e32 v207, 0xffff0000, v110
	v_lshlrev_b32_e32 v208, 16, v111
	v_and_b32_e32 v209, 0xffff0000, v111
	v_lshlrev_b32_e32 v210, 16, v78
	v_and_b32_e32 v211, 0xffff0000, v78
	v_lshlrev_b32_e32 v212, 16, v79
	v_and_b32_e32 v213, 0xffff0000, v79
	v_pk_fma_f32 v[210:211], v[26:27], v[206:207], v[210:211]
	v_pk_fma_f32 v[212:213], v[28:29], v[208:209], v[212:213]
	v_cvt_pk_bf16_f32 v78, v210, v211
	v_cvt_pk_bf16_f32 v79, v212, v213
	v_lshlrev_b32_e32 v206, 16, v112
	v_and_b32_e32 v207, 0xffff0000, v112
	v_lshlrev_b32_e32 v208, 16, v113
	v_and_b32_e32 v209, 0xffff0000, v113
	v_lshlrev_b32_e32 v210, 16, v80
	v_and_b32_e32 v211, 0xffff0000, v80
	v_lshlrev_b32_e32 v212, 16, v81
	v_and_b32_e32 v213, 0xffff0000, v81
	v_pk_fma_f32 v[210:211], v[30:31], v[206:207], v[210:211]
	v_pk_fma_f32 v[212:213], v[32:33], v[208:209], v[212:213]
	v_cvt_pk_bf16_f32 v80, v210, v211
	v_cvt_pk_bf16_f32 v81, v212, v213
	v_lshlrev_b32_e32 v206, 16, v114
	v_and_b32_e32 v207, 0xffff0000, v114
	v_lshlrev_b32_e32 v208, 16, v115
	v_and_b32_e32 v209, 0xffff0000, v115
	v_lshlrev_b32_e32 v210, 16, v82
	v_and_b32_e32 v211, 0xffff0000, v82
	v_lshlrev_b32_e32 v212, 16, v83
	v_and_b32_e32 v213, 0xffff0000, v83
	v_pk_fma_f32 v[210:211], v[34:35], v[206:207], v[210:211]
	v_pk_fma_f32 v[212:213], v[36:37], v[208:209], v[212:213]
	v_cvt_pk_bf16_f32 v82, v210, v211
	v_cvt_pk_bf16_f32 v83, v212, v213
	v_lshlrev_b32_e32 v206, 16, v116
	v_and_b32_e32 v207, 0xffff0000, v116
	v_lshlrev_b32_e32 v208, 16, v117
	v_and_b32_e32 v209, 0xffff0000, v117
	v_lshlrev_b32_e32 v210, 16, v84
	v_and_b32_e32 v211, 0xffff0000, v84
	v_lshlrev_b32_e32 v212, 16, v85
	v_and_b32_e32 v213, 0xffff0000, v85
	v_pk_fma_f32 v[210:211], v[38:39], v[206:207], v[210:211]
	v_pk_fma_f32 v[212:213], v[40:41], v[208:209], v[212:213]
	v_cvt_pk_bf16_f32 v84, v210, v211
	v_cvt_pk_bf16_f32 v85, v212, v213
	v_lshlrev_b32_e32 v206, 16, v118
	v_and_b32_e32 v207, 0xffff0000, v118
	v_lshlrev_b32_e32 v208, 16, v119
	v_and_b32_e32 v209, 0xffff0000, v119
	v_lshlrev_b32_e32 v210, 16, v86
	v_and_b32_e32 v211, 0xffff0000, v86
	v_lshlrev_b32_e32 v212, 16, v87
	v_and_b32_e32 v213, 0xffff0000, v87
	v_pk_fma_f32 v[210:211], v[42:43], v[206:207], v[210:211]
	v_pk_fma_f32 v[212:213], v[44:45], v[208:209], v[212:213]
	v_cvt_pk_bf16_f32 v86, v210, v211
	v_cvt_pk_bf16_f32 v87, v212, v213
	v_lshlrev_b32_e32 v206, 16, v120
	v_and_b32_e32 v207, 0xffff0000, v120
	v_lshlrev_b32_e32 v208, 16, v121
	v_and_b32_e32 v209, 0xffff0000, v121
	v_lshlrev_b32_e32 v210, 16, v88
	v_and_b32_e32 v211, 0xffff0000, v88
	v_lshlrev_b32_e32 v212, 16, v89
	v_and_b32_e32 v213, 0xffff0000, v89
	v_pk_fma_f32 v[210:211], v[46:47], v[206:207], v[210:211]
	v_pk_fma_f32 v[212:213], v[48:49], v[208:209], v[212:213]
	v_cvt_pk_bf16_f32 v88, v210, v211
	v_cvt_pk_bf16_f32 v89, v212, v213
	v_lshlrev_b32_e32 v206, 16, v122
	v_and_b32_e32 v207, 0xffff0000, v122
	v_lshlrev_b32_e32 v208, 16, v123
	v_and_b32_e32 v209, 0xffff0000, v123
	v_lshlrev_b32_e32 v210, 16, v90
	v_and_b32_e32 v211, 0xffff0000, v90
	v_lshlrev_b32_e32 v212, 16, v91
	v_and_b32_e32 v213, 0xffff0000, v91
	v_pk_fma_f32 v[210:211], v[50:51], v[206:207], v[210:211]
	v_pk_fma_f32 v[212:213], v[52:53], v[208:209], v[212:213]
	v_cvt_pk_bf16_f32 v90, v210, v211
	v_cvt_pk_bf16_f32 v91, v212, v213
	v_lshlrev_b32_e32 v206, 16, v124
	v_and_b32_e32 v207, 0xffff0000, v124
	v_lshlrev_b32_e32 v208, 16, v125
	v_and_b32_e32 v209, 0xffff0000, v125
	v_lshlrev_b32_e32 v210, 16, v92
	v_and_b32_e32 v211, 0xffff0000, v92
	v_lshlrev_b32_e32 v212, 16, v93
	v_and_b32_e32 v213, 0xffff0000, v93
	v_pk_fma_f32 v[210:211], v[54:55], v[206:207], v[210:211]
	v_pk_fma_f32 v[212:213], v[56:57], v[208:209], v[212:213]
	v_cvt_pk_bf16_f32 v92, v210, v211
	v_cvt_pk_bf16_f32 v93, v212, v213
	v_lshlrev_b32_e32 v206, 16, v126
	v_and_b32_e32 v207, 0xffff0000, v126
	v_lshlrev_b32_e32 v208, 16, v127
	v_and_b32_e32 v209, 0xffff0000, v127
	v_lshlrev_b32_e32 v210, 16, v94
	v_and_b32_e32 v211, 0xffff0000, v94
	v_lshlrev_b32_e32 v212, 16, v95
	v_and_b32_e32 v213, 0xffff0000, v95
	v_pk_fma_f32 v[210:211], v[58:59], v[206:207], v[210:211]
	v_pk_fma_f32 v[212:213], v[60:61], v[208:209], v[212:213]
	v_cvt_pk_bf16_f32 v94, v210, v211
	v_cvt_pk_bf16_f32 v95, v212, v213
	v_lshlrev_b32_e32 v206, 16, v128
	v_and_b32_e32 v207, 0xffff0000, v128
	v_lshlrev_b32_e32 v208, 16, v129
	v_and_b32_e32 v209, 0xffff0000, v129
	v_lshlrev_b32_e32 v210, 16, v96
	v_and_b32_e32 v211, 0xffff0000, v96
	v_lshlrev_b32_e32 v212, 16, v97
	v_and_b32_e32 v213, 0xffff0000, v97
	v_pk_fma_f32 v[210:211], v[62:63], v[206:207], v[210:211]
	v_pk_fma_f32 v[212:213], v[64:65], v[208:209], v[212:213]
	v_cvt_pk_bf16_f32 v96, v210, v211
	v_cvt_pk_bf16_f32 v97, v212, v213
	s_add_u32 s66, s64, 0x300
	s_addc_u32 s67, s65, 0
	s_add_u32 s70, s68, 0x80100
	s_addc_u32 s71, s69, 0
	s_add_u32 s72, s70, 0x10000
	s_addc_u32 s73, s71, 0
	s_add_i32 m0, s78, 0x0
	s_nop 0
	global_load_lds_dwordx4 v197, s[66:67]
	s_add_i32 m0, s78, 0x2000
	s_nop 0
	global_load_lds_dwordx4 v198, s[66:67]
	s_add_i32 m0, s78, 0x4000
	s_nop 0
	global_load_lds_dwordx4 v199, s[70:71]
	s_add_i32 m0, s78, 0x6000
	s_nop 0
	global_load_lds_dwordx4 v200, s[70:71]
	s_add_i32 m0, s78, 0x8000
	s_nop 0
	global_load_lds_dwordx4 v199, s[72:73]
	s_add_i32 m0, s78, 0xa000
	s_nop 0
	global_load_lds_dwordx4 v200, s[72:73]
	ds_read_b128 v[130:133], v215 offset:0
	ds_read_b128 v[134:137], v215 offset:2048
	ds_read_b128 v[138:141], v215 offset:4096
	ds_read_b128 v[142:145], v215 offset:6144
	ds_read_b128 v[162:165], v218 offset:0
	ds_read_b128 v[166:169], v218 offset:2048
	ds_read_b128 v[170:173], v218 offset:4096
	ds_read_b128 v[174:177], v218 offset:6144
	ds_read_b128 v[146:149], v215 offset:1024
	ds_read_b128 v[150:153], v215 offset:3072
	ds_read_b128 v[154:157], v215 offset:5120
	ds_read_b128 v[158:161], v215 offset:7168
	ds_read_b128 v[178:181], v218 offset:1024
	ds_read_b128 v[182:185], v218 offset:3072
	ds_read_b128 v[186:189], v218 offset:5120
	ds_read_b128 v[190:193], v218 offset:7168
	s_waitcnt lgkmcnt(8)
; #define LAS __attribute__((address_space(3)))
; __device__ __forceinline__ void branch_phase(LAS unsigned char* lds, const bf16_t* __restrict__ O, const bf16_t* __restrict__ Wb, const bf16_t* __restrict__ Gt, bf16_t* __restrict__ MG, int tg, int wv) {
;     ...
;         for (int j = 0; j < 4; ++j) {
;             u32x2 gv[4][4];
;             f32x4 acc[4][4];
; #pragma unroll
;             for (int m = 0; m < 4; ++m)
; #pragma unroll
;                 for (int n = 0; n < 4; ++n) acc[m][n] = (f32x4){0.f, 0.f, 0.f, 0.f};
;             for (int kc = 0; kc < 4; ++kc) {
;                 const int c = j * 4 + kc;
;                 if (c + 1 < 16) BR_LOAD(c + 1, (c + 1) & 1);
;                 if (kc == 3) {
;                     const bf16_t* gp = Gt + (size_t)(rt * 128 + wm * 64 + fr) * ZC + j * 1024 + ct * 256 + wn * 64 + 4 * fq;
; #pragma unroll
;                     for (int m = 0; m < 4; ++m)
; #pragma unroll
;                         for (int n = 0; n < 4; ++n) gv[m][n] = *(const u32x2*)(gp + (size_t)m * 16 * ZC + n * 16);
;                 }
;                 LAS const unsigned char* st = lds + (c & 1) * STG;
; #pragma unroll
;                 for (int k = 0; k < 2; ++k) {
;                     __builtin_amdgcn_sched_barrier(0);
;                     bf16x8 af[4], bfr[4];
; #pragma unroll
;                     for (int m = 0; m < 4; ++m) af[m] = *(LAS const bf16x8*)(st + aoff + m * 2048 + k * 1024);
; #pragma unroll
;                     for (int n = 0; n < 4; ++n) bfr[n] = *(LAS const bf16x8*)(st + boff + n * 2048 + k * 1024);
; #pragma unroll
;                     for (int m = 0; m < 4; ++m)
; #pragma unroll
;                         for (int n = 0; n < 4; ++n) acc[m][n] = __builtin_amdgcn_mfma_f32_16x16x32_bf16(bfr[n], af[m], acc[m][n], 0, 0, 0);
;                 }
;                 asm volatile("s_waitcnt vmcnt(0)" ::: "memory"); __syncthreads();
	v_mfma_f32_16x16x32_bf16 v[2:5], v[162:165], v[130:133], 0
	v_mfma_f32_16x16x32_bf16 v[6:9], v[166:169], v[130:133], 0
	v_mfma_f32_16x16x32_bf16 v[10:13], v[170:173], v[130:133], 0
	v_mfma_f32_16x16x32_bf16 v[14:17], v[174:177], v[130:133], 0
	v_mfma_f32_16x16x32_bf16 v[18:21], v[162:165], v[134:137], 0
	v_mfma_f32_16x16x32_bf16 v[22:25], v[166:169], v[134:137], 0
	v_mfma_f32_16x16x32_bf16 v[26:29], v[170:173], v[134:137], 0
	v_mfma_f32_16x16x32_bf16 v[30:33], v[174:177], v[134:137], 0
	v_mfma_f32_16x16x32_bf16 v[34:37], v[162:165], v[138:141], 0
	v_mfma_f32_16x16x32_bf16 v[38:41], v[166:169], v[138:141], 0
	v_mfma_f32_16x16x32_bf16 v[42:45], v[170:173], v[138:141], 0
	v_mfma_f32_16x16x32_bf16 v[46:49], v[174:177], v[138:141], 0
	v_mfma_f32_16x16x32_bf16 v[50:53], v[162:165], v[142:145], 0
	v_mfma_f32_16x16x32_bf16 v[54:57], v[166:169], v[142:145], 0
	v_mfma_f32_16x16x32_bf16 v[58:61], v[170:173], v[142:145], 0
	v_mfma_f32_16x16x32_bf16 v[62:65], v[174:177], v[142:145], 0
	s_waitcnt lgkmcnt(0)
	v_mfma_f32_16x16x32_bf16 v[2:5], v[178:181], v[146:149], v[2:5]
	v_mfma_f32_16x16x32_bf16 v[6:9], v[182:185], v[146:149], v[6:9]
	v_mfma_f32_16x16x32_bf16 v[10:13], v[186:189], v[146:149], v[10:13]
	v_mfma_f32_16x16x32_bf16 v[14:17], v[190:193], v[146:149], v[14:17]
	v_mfma_f32_16x16x32_bf16 v[18:21], v[178:181], v[150:153], v[18:21]
	v_mfma_f32_16x16x32_bf16 v[22:25], v[182:185], v[150:153], v[22:25]
	v_mfma_f32_16x16x32_bf16 v[26:29], v[186:189], v[150:153], v[26:29]
	v_mfma_f32_16x16x32_bf16 v[30:33], v[190:193], v[150:153], v[30:33]
	v_mfma_f32_16x16x32_bf16 v[34:37], v[178:181], v[154:157], v[34:37]
	v_mfma_f32_16x16x32_bf16 v[38:41], v[182:185], v[154:157], v[38:41]
	v_mfma_f32_16x16x32_bf16 v[42:45], v[186:189], v[154:157], v[42:45]
	v_mfma_f32_16x16x32_bf16 v[46:49], v[190:193], v[154:157], v[46:49]
	v_mfma_f32_16x16x32_bf16 v[50:53], v[178:181], v[158:161], v[50:53]
	v_mfma_f32_16x16x32_bf16 v[54:57], v[182:185], v[158:161], v[54:57]
	v_mfma_f32_16x16x32_bf16 v[58:61], v[186:189], v[158:161], v[58:61]
	v_mfma_f32_16x16x32_bf16 v[62:65], v[190:193], v[158:161], v[62:65]
	s_waitcnt vmcnt(6)
	s_barrier
	s_add_u32 s66, s64, 0x380
	s_addc_u32 s67, s65, 0
	s_add_u32 s70, s68, 0x80180
	s_addc_u32 s71, s69, 0
	s_add_u32 s72, s70, 0x10000
	s_addc_u32 s73, s71, 0
	s_add_i32 m0, s78, 0xc000
	s_nop 0
	global_load_lds_dwordx4 v197, s[66:67]
	s_add_i32 m0, s78, 0xe000
	s_nop 0
	global_load_lds_dwordx4 v198, s[66:67]
	s_add_i32 m0, s78, 0x10000
	s_nop 0
	global_load_lds_dwordx4 v199, s[70:71]
	s_add_i32 m0, s78, 0x12000
	s_nop 0
	global_load_lds_dwordx4 v200, s[70:71]
	s_add_i32 m0, s78, 0x14000
	s_nop 0
	global_load_lds_dwordx4 v199, s[72:73]
	s_add_i32 m0, s78, 0x16000
	s_nop 0
	global_load_lds_dwordx4 v200, s[72:73]
	s_add_u32 s80, s74, 0x800
	s_addc_u32 s81, s75, 0
	global_load_dwordx2 v[98:99], v204, s[80:81] offset:0
	global_load_dwordx2 v[100:101], v204, s[80:81] offset:32
	global_load_dwordx2 v[102:103], v204, s[80:81] offset:64
	global_load_dwordx2 v[104:105], v204, s[80:81] offset:96
	s_add_u32 s80, s80, 0x20000
	s_addc_u32 s81, s81, 0
	global_load_dwordx2 v[106:107], v204, s[80:81] offset:0
	global_load_dwordx2 v[108:109], v204, s[80:81] offset:32
	global_load_dwordx2 v[110:111], v204, s[80:81] offset:64
	global_load_dwordx2 v[112:113], v204, s[80:81] offset:96
	s_add_u32 s80, s80, 0x20000
	s_addc_u32 s81, s81, 0
	global_load_dwordx2 v[114:115], v204, s[80:81] offset:0
	global_load_dwordx2 v[116:117], v204, s[80:81] offset:32
	global_load_dwordx2 v[118:119], v204, s[80:81] offset:64
	global_load_dwordx2 v[120:121], v204, s[80:81] offset:96
	s_add_u32 s80, s80, 0x20000
	s_addc_u32 s81, s81, 0
	global_load_dwordx2 v[122:123], v204, s[80:81] offset:0
	global_load_dwordx2 v[124:125], v204, s[80:81] offset:32
	global_load_dwordx2 v[126:127], v204, s[80:81] offset:64
	global_load_dwordx2 v[128:129], v204, s[80:81] offset:96
	ds_read_b128 v[130:133], v216 offset:0
	ds_read_b128 v[134:137], v216 offset:2048
	ds_read_b128 v[138:141], v216 offset:4096
	ds_read_b128 v[142:145], v216 offset:6144
	ds_read_b128 v[162:165], v219 offset:0
	ds_read_b128 v[166:169], v219 offset:2048
	ds_read_b128 v[170:173], v219 offset:4096
	ds_read_b128 v[174:177], v219 offset:6144
	ds_read_b128 v[146:149], v216 offset:1024
	ds_read_b128 v[150:153], v216 offset:3072
	ds_read_b128 v[154:157], v216 offset:5120
	ds_read_b128 v[158:161], v216 offset:7168
	ds_read_b128 v[178:181], v219 offset:1024
	ds_read_b128 v[182:185], v219 offset:3072
	ds_read_b128 v[186:189], v219 offset:5120
	ds_read_b128 v[190:193], v219 offset:7168
	s_waitcnt lgkmcnt(8)
	v_mfma_f32_16x16x32_bf16 v[2:5], v[162:165], v[130:133], v[2:5]
	v_mfma_f32_16x16x32_bf16 v[6:9], v[166:169], v[130:133], v[6:9]
	v_mfma_f32_16x16x32_bf16 v[10:13], v[170:173], v[130:133], v[10:13]
	v_mfma_f32_16x16x32_bf16 v[14:17], v[174:177], v[130:133], v[14:17]
	v_mfma_f32_16x16x32_bf16 v[18:21], v[162:165], v[134:137], v[18:21]
	v_mfma_f32_16x16x32_bf16 v[22:25], v[166:169], v[134:137], v[22:25]
	v_mfma_f32_16x16x32_bf16 v[26:29], v[170:173], v[134:137], v[26:29]
	v_mfma_f32_16x16x32_bf16 v[30:33], v[174:177], v[134:137], v[30:33]
	v_mfma_f32_16x16x32_bf16 v[34:37], v[162:165], v[138:141], v[34:37]
	v_mfma_f32_16x16x32_bf16 v[38:41], v[166:169], v[138:141], v[38:41]
	v_mfma_f32_16x16x32_bf16 v[42:45], v[170:173], v[138:141], v[42:45]
	v_mfma_f32_16x16x32_bf16 v[46:49], v[174:177], v[138:141], v[46:49]
	v_mfma_f32_16x16x32_bf16 v[50:53], v[162:165], v[142:145], v[50:53]
	v_mfma_f32_16x16x32_bf16 v[54:57], v[166:169], v[142:145], v[54:57]
	v_mfma_f32_16x16x32_bf16 v[58:61], v[170:173], v[142:145], v[58:61]
	v_mfma_f32_16x16x32_bf16 v[62:65], v[174:177], v[142:145], v[62:65]
	s_waitcnt lgkmcnt(0)
	v_mfma_f32_16x16x32_bf16 v[2:5], v[178:181], v[146:149], v[2:5]
	v_mfma_f32_16x16x32_bf16 v[6:9], v[182:185], v[146:149], v[6:9]
	v_mfma_f32_16x16x32_bf16 v[10:13], v[186:189], v[146:149], v[10:13]
	v_mfma_f32_16x16x32_bf16 v[14:17], v[190:193], v[146:149], v[14:17]
	v_mfma_f32_16x16x32_bf16 v[18:21], v[178:181], v[150:153], v[18:21]
	v_mfma_f32_16x16x32_bf16 v[22:25], v[182:185], v[150:153], v[22:25]
	v_mfma_f32_16x16x32_bf16 v[26:29], v[186:189], v[150:153], v[26:29]
	v_mfma_f32_16x16x32_bf16 v[30:33], v[190:193], v[150:153], v[30:33]
	v_mfma_f32_16x16x32_bf16 v[34:37], v[178:181], v[154:157], v[34:37]
	v_mfma_f32_16x16x32_bf16 v[38:41], v[182:185], v[154:157], v[38:41]
	v_mfma_f32_16x16x32_bf16 v[42:45], v[186:189], v[154:157], v[42:45]
	v_mfma_f32_16x16x32_bf16 v[46:49], v[190:193], v[154:157], v[46:49]
	v_mfma_f32_16x16x32_bf16 v[50:53], v[178:181], v[158:161], v[50:53]
	v_mfma_f32_16x16x32_bf16 v[54:57], v[182:185], v[158:161], v[54:57]
	v_mfma_f32_16x16x32_bf16 v[58:61], v[186:189], v[158:161], v[58:61]
	v_mfma_f32_16x16x32_bf16 v[62:65], v[190:193], v[158:161], v[62:65]
	s_waitcnt vmcnt(22)
	s_barrier
; #define LAS __attribute__((address_space(3)))
; __device__ __forceinline__ void branch_phase(LAS unsigned char* lds, const bf16_t* __restrict__ O, const bf16_t* __restrict__ Wb, const bf16_t* __restrict__ Gt, bf16_t* __restrict__ MG, int tg, int wv) {
;     ...
;             for (int kc = 0; kc < 4; ++kc) {
;                 const int c = j * 4 + kc;
;                 if (c + 1 < 16) BR_LOAD(c + 1, (c + 1) & 1);
;                 if (kc == 3) {
;                     const bf16_t* gp = Gt + (size_t)(rt * 128 + wm * 64 + fr) * ZC + j * 1024 + ct * 256 + wn * 64 + 4 * fq;
; #pragma unroll
;                     for (int m = 0; m < 4; ++m)
; #pragma unroll
;                         for (int n = 0; n < 4; ++n) gv[m][n] = *(const u32x2*)(gp + (size_t)m * 16 * ZC + n * 16);
;                 }
;                 LAS const unsigned char* st = lds + (c & 1) * STG;
; #pragma unroll
;                 for (int k = 0; k < 2; ++k) {
;                     __builtin_amdgcn_sched_barrier(0);
;                     bf16x8 af[4], bfr[4];
; #pragma unroll
;                     for (int m = 0; m < 4; ++m) af[m] = *(LAS const bf16x8*)(st + aoff + m * 2048 + k * 1024);
; #pragma unroll
;                     for (int n = 0; n < 4; ++n) bfr[n] = *(LAS const bf16x8*)(st + boff + n * 2048 + k * 1024);
; #pragma unroll
;                     for (int m = 0; m < 4; ++m)
; #pragma unroll
;                         for (int n = 0; n < 4; ++n) acc[m][n] = __builtin_amdgcn_mfma_f32_16x16x32_bf16(bfr[n], af[m], acc[m][n], 0, 0, 0);
;                 }
;                 asm volatile("s_waitcnt vmcnt(0)" ::: "memory"); __syncthreads();
	s_add_u32 s66, s64, 0x400
	s_addc_u32 s67, s65, 0
	s_add_u32 s70, s68, 0x100000
	s_addc_u32 s71, s69, 0
	s_add_u32 s72, s70, 0x10000
	s_addc_u32 s73, s71, 0
	s_add_i32 m0, s78, 0x18000
	s_nop 0
	global_load_lds_dwordx4 v197, s[66:67]
	s_add_i32 m0, s78, 0x1a000
	s_nop 0
	global_load_lds_dwordx4 v198, s[66:67]
	s_add_i32 m0, s78, 0x1c000
	s_nop 0
	global_load_lds_dwordx4 v199, s[70:71]
	s_add_i32 m0, s78, 0x1e000
	s_nop 0
	global_load_lds_dwordx4 v200, s[70:71]
	s_add_i32 m0, s78, 0x20800
	s_nop 0
	global_load_lds_dwordx4 v199, s[72:73]
	s_add_i32 m0, s78, 0x22800
	s_nop 0
	global_load_lds_dwordx4 v200, s[72:73]
	ds_read_b128 v[130:133], v214 offset:0
	ds_read_b128 v[134:137], v214 offset:2048
	ds_read_b128 v[138:141], v214 offset:4096
	ds_read_b128 v[142:145], v214 offset:6144
	ds_read_b128 v[162:165], v217 offset:0
	ds_read_b128 v[166:169], v217 offset:2048
	ds_read_b128 v[170:173], v217 offset:4096
	ds_read_b128 v[174:177], v217 offset:6144
	ds_read_b128 v[146:149], v214 offset:1024
	ds_read_b128 v[150:153], v214 offset:3072
	ds_read_b128 v[154:157], v214 offset:5120
	ds_read_b128 v[158:161], v214 offset:7168
	ds_read_b128 v[178:181], v217 offset:1024
	ds_read_b128 v[182:185], v217 offset:3072
	ds_read_b128 v[186:189], v217 offset:5120
	ds_read_b128 v[190:193], v217 offset:7168
	s_waitcnt lgkmcnt(8)
	v_mfma_f32_16x16x32_bf16 v[2:5], v[162:165], v[130:133], v[2:5]
	v_mfma_f32_16x16x32_bf16 v[6:9], v[166:169], v[130:133], v[6:9]
	v_mfma_f32_16x16x32_bf16 v[10:13], v[170:173], v[130:133], v[10:13]
	v_mfma_f32_16x16x32_bf16 v[14:17], v[174:177], v[130:133], v[14:17]
	v_mfma_f32_16x16x32_bf16 v[18:21], v[162:165], v[134:137], v[18:21]
	v_mfma_f32_16x16x32_bf16 v[22:25], v[166:169], v[134:137], v[22:25]
	v_mfma_f32_16x16x32_bf16 v[26:29], v[170:173], v[134:137], v[26:29]
	v_mfma_f32_16x16x32_bf16 v[30:33], v[174:177], v[134:137], v[30:33]
	v_mfma_f32_16x16x32_bf16 v[34:37], v[162:165], v[138:141], v[34:37]
	v_mfma_f32_16x16x32_bf16 v[38:41], v[166:169], v[138:141], v[38:41]
	v_mfma_f32_16x16x32_bf16 v[42:45], v[170:173], v[138:141], v[42:45]
	v_mfma_f32_16x16x32_bf16 v[46:49], v[174:177], v[138:141], v[46:49]
	v_mfma_f32_16x16x32_bf16 v[50:53], v[162:165], v[142:145], v[50:53]
	v_mfma_f32_16x16x32_bf16 v[54:57], v[166:169], v[142:145], v[54:57]
	v_mfma_f32_16x16x32_bf16 v[58:61], v[170:173], v[142:145], v[58:61]
	v_mfma_f32_16x16x32_bf16 v[62:65], v[174:177], v[142:145], v[62:65]
	s_waitcnt lgkmcnt(0)
	v_mfma_f32_16x16x32_bf16 v[2:5], v[178:181], v[146:149], v[2:5]
	v_mfma_f32_16x16x32_bf16 v[6:9], v[182:185], v[146:149], v[6:9]
	v_mfma_f32_16x16x32_bf16 v[10:13], v[186:189], v[146:149], v[10:13]
	v_mfma_f32_16x16x32_bf16 v[14:17], v[190:193], v[146:149], v[14:17]
	v_mfma_f32_16x16x32_bf16 v[18:21], v[178:181], v[150:153], v[18:21]
	v_mfma_f32_16x16x32_bf16 v[22:25], v[182:185], v[150:153], v[22:25]
	v_mfma_f32_16x16x32_bf16 v[26:29], v[186:189], v[150:153], v[26:29]
	v_mfma_f32_16x16x32_bf16 v[30:33], v[190:193], v[150:153], v[30:33]
	v_mfma_f32_16x16x32_bf16 v[34:37], v[178:181], v[154:157], v[34:37]
	v_mfma_f32_16x16x32_bf16 v[38:41], v[182:185], v[154:157], v[38:41]
	v_mfma_f32_16x16x32_bf16 v[42:45], v[186:189], v[154:157], v[42:45]
	v_mfma_f32_16x16x32_bf16 v[46:49], v[190:193], v[154:157], v[46:49]
	v_mfma_f32_16x16x32_bf16 v[50:53], v[178:181], v[158:161], v[50:53]
	v_mfma_f32_16x16x32_bf16 v[54:57], v[182:185], v[158:161], v[54:57]
	v_mfma_f32_16x16x32_bf16 v[58:61], v[186:189], v[158:161], v[58:61]
	v_mfma_f32_16x16x32_bf16 v[62:65], v[190:193], v[158:161], v[62:65]
	s_waitcnt vmcnt(22)
	s_barrier
	s_add_u32 s66, s64, 0x480
	s_addc_u32 s67, s65, 0
	s_add_u32 s70, s68, 0x100080
	s_addc_u32 s71, s69, 0
	s_add_u32 s72, s70, 0x10000
	s_addc_u32 s73, s71, 0
	s_add_i32 m0, s78, 0x0
	s_nop 0
	global_load_lds_dwordx4 v197, s[66:67]
	s_add_i32 m0, s78, 0x2000
	s_nop 0
	global_load_lds_dwordx4 v198, s[66:67]
	s_add_i32 m0, s78, 0x4000
	s_nop 0
	global_load_lds_dwordx4 v199, s[70:71]
	s_add_i32 m0, s78, 0x6000
	s_nop 0
	global_load_lds_dwordx4 v200, s[70:71]
	s_add_i32 m0, s78, 0x8000
	s_nop 0
	global_load_lds_dwordx4 v199, s[72:73]
	s_add_i32 m0, s78, 0xa000
	s_nop 0
	global_load_lds_dwordx4 v200, s[72:73]
	ds_read_b128 v[130:133], v215 offset:0
	ds_read_b128 v[134:137], v215 offset:2048
	ds_read_b128 v[138:141], v215 offset:4096
	ds_read_b128 v[142:145], v215 offset:6144
	ds_read_b128 v[162:165], v218 offset:0
	ds_read_b128 v[166:169], v218 offset:2048
	ds_read_b128 v[170:173], v218 offset:4096
	ds_read_b128 v[174:177], v218 offset:6144
	ds_read_b128 v[146:149], v215 offset:1024
	ds_read_b128 v[150:153], v215 offset:3072
	ds_read_b128 v[154:157], v215 offset:5120
	ds_read_b128 v[158:161], v215 offset:7168
	ds_read_b128 v[178:181], v218 offset:1024
	ds_read_b128 v[182:185], v218 offset:3072
	ds_read_b128 v[186:189], v218 offset:5120
	ds_read_b128 v[190:193], v218 offset:7168
	s_waitcnt lgkmcnt(8)
	v_mfma_f32_16x16x32_bf16 v[2:5], v[162:165], v[130:133], v[2:5]
	v_mfma_f32_16x16x32_bf16 v[6:9], v[166:169], v[130:133], v[6:9]
	v_mfma_f32_16x16x32_bf16 v[10:13], v[170:173], v[130:133], v[10:13]
	v_mfma_f32_16x16x32_bf16 v[14:17], v[174:177], v[130:133], v[14:17]
	v_mfma_f32_16x16x32_bf16 v[18:21], v[162:165], v[134:137], v[18:21]
	v_mfma_f32_16x16x32_bf16 v[22:25], v[166:169], v[134:137], v[22:25]
	v_mfma_f32_16x16x32_bf16 v[26:29], v[170:173], v[134:137], v[26:29]
	v_mfma_f32_16x16x32_bf16 v[30:33], v[174:177], v[134:137], v[30:33]
	v_mfma_f32_16x16x32_bf16 v[34:37], v[162:165], v[138:141], v[34:37]
	v_mfma_f32_16x16x32_bf16 v[38:41], v[166:169], v[138:141], v[38:41]
	v_mfma_f32_16x16x32_bf16 v[42:45], v[170:173], v[138:141], v[42:45]
	v_mfma_f32_16x16x32_bf16 v[46:49], v[174:177], v[138:141], v[46:49]
	v_mfma_f32_16x16x32_bf16 v[50:53], v[162:165], v[142:145], v[50:53]
	v_mfma_f32_16x16x32_bf16 v[54:57], v[166:169], v[142:145], v[54:57]
	v_mfma_f32_16x16x32_bf16 v[58:61], v[170:173], v[142:145], v[58:61]
	v_mfma_f32_16x16x32_bf16 v[62:65], v[174:177], v[142:145], v[62:65]
	s_waitcnt lgkmcnt(0)
; #define LAS __attribute__((address_space(3)))
; __device__ __forceinline__ unsigned cvtpk(float lo, float hi) { f32x2 v = {lo, hi}; bf16x2_t b = __builtin_convertvector(v, bf16x2_t); return __builtin_bit_cast(unsigned, b); }
; __device__ __forceinline__ void branch_phase(LAS unsigned char* lds, const bf16_t* __restrict__ O, const bf16_t* __restrict__ Wb, const bf16_t* __restrict__ Gt, bf16_t* __restrict__ MG, int tg, int wv) {
;     ...
;                     for (int m = 0; m < 4; ++m) af[m] = *(LAS const bf16x8*)(st + aoff + m * 2048 + k * 1024);
; #pragma unroll
;                     for (int n = 0; n < 4; ++n) bfr[n] = *(LAS const bf16x8*)(st + boff + n * 2048 + k * 1024);
; #pragma unroll
;                     for (int m = 0; m < 4; ++m)
; #pragma unroll
;                         for (int n = 0; n < 4; ++n) acc[m][n] = __builtin_amdgcn_mfma_f32_16x16x32_bf16(bfr[n], af[m], acc[m][n], 0, 0, 0);
;                 }
;                 asm volatile("s_waitcnt vmcnt(0)" ::: "memory"); __syncthreads();
;             }
; #pragma unroll
;             for (int m = 0; m < 4; ++m)
; #pragma unroll
;                 for (int n = 0; n < 4; ++n) { const u32x2 g = gv[m][n], sp = sum[m][n];
;                     const float s0_ = __builtin_bit_cast(float, sp.x << 16) + acc[m][n][0] * __builtin_bit_cast(float, g.x << 16), s1_ = __builtin_bit_cast(float, sp.x & 0xffff0000u) + acc[m][n][1] * __builtin_bit_cast(float, g.x & 0xffff0000u);
;                     const float s2_ = __builtin_bit_cast(float, sp.y << 16) + acc[m][n][2] * __builtin_bit_cast(float, g.y << 16), s3_ = __builtin_bit_cast(float, sp.y & 0xffff0000u) + acc[m][n][3] * __builtin_bit_cast(float, g.y & 0xffff0000u);
;                     sum[m][n] = (u32x2){cvtpk(s0_, s1_), cvtpk(s2_, s3_)}; }
	v_mfma_f32_16x16x32_bf16 v[2:5], v[178:181], v[146:149], v[2:5]
	v_mfma_f32_16x16x32_bf16 v[6:9], v[182:185], v[146:149], v[6:9]
	v_mfma_f32_16x16x32_bf16 v[10:13], v[186:189], v[146:149], v[10:13]
	v_mfma_f32_16x16x32_bf16 v[14:17], v[190:193], v[146:149], v[14:17]
	v_mfma_f32_16x16x32_bf16 v[18:21], v[178:181], v[150:153], v[18:21]
	v_mfma_f32_16x16x32_bf16 v[22:25], v[182:185], v[150:153], v[22:25]
	v_mfma_f32_16x16x32_bf16 v[26:29], v[186:189], v[150:153], v[26:29]
	v_mfma_f32_16x16x32_bf16 v[30:33], v[190:193], v[150:153], v[30:33]
	v_mfma_f32_16x16x32_bf16 v[34:37], v[178:181], v[154:157], v[34:37]
	v_mfma_f32_16x16x32_bf16 v[38:41], v[182:185], v[154:157], v[38:41]
	v_mfma_f32_16x16x32_bf16 v[42:45], v[186:189], v[154:157], v[42:45]
	v_mfma_f32_16x16x32_bf16 v[46:49], v[190:193], v[154:157], v[46:49]
	v_mfma_f32_16x16x32_bf16 v[50:53], v[178:181], v[158:161], v[50:53]
	v_mfma_f32_16x16x32_bf16 v[54:57], v[182:185], v[158:161], v[54:57]
	v_mfma_f32_16x16x32_bf16 v[58:61], v[186:189], v[158:161], v[58:61]
	v_mfma_f32_16x16x32_bf16 v[62:65], v[190:193], v[158:161], v[62:65]
	s_waitcnt vmcnt(6)
	s_barrier
	s_nop 7
	v_lshlrev_b32_e32 v206, 16, v98
	v_and_b32_e32 v207, 0xffff0000, v98
	v_lshlrev_b32_e32 v208, 16, v99
	v_and_b32_e32 v209, 0xffff0000, v99
	v_lshlrev_b32_e32 v210, 16, v66
	v_and_b32_e32 v211, 0xffff0000, v66
	v_lshlrev_b32_e32 v212, 16, v67
	v_and_b32_e32 v213, 0xffff0000, v67
	v_pk_fma_f32 v[210:211], v[2:3], v[206:207], v[210:211]
	v_pk_fma_f32 v[212:213], v[4:5], v[208:209], v[212:213]
	v_cvt_pk_bf16_f32 v66, v210, v211
	v_cvt_pk_bf16_f32 v67, v212, v213
	v_lshlrev_b32_e32 v206, 16, v100
	v_and_b32_e32 v207, 0xffff0000, v100
	v_lshlrev_b32_e32 v208, 16, v101
	v_and_b32_e32 v209, 0xffff0000, v101
	v_lshlrev_b32_e32 v210, 16, v68
	v_and_b32_e32 v211, 0xffff0000, v68
	v_lshlrev_b32_e32 v212, 16, v69
	v_and_b32_e32 v213, 0xffff0000, v69
	v_pk_fma_f32 v[210:211], v[6:7], v[206:207], v[210:211]
	v_pk_fma_f32 v[212:213], v[8:9], v[208:209], v[212:213]
	v_cvt_pk_bf16_f32 v68, v210, v211
	v_cvt_pk_bf16_f32 v69, v212, v213
	v_lshlrev_b32_e32 v206, 16, v102
	v_and_b32_e32 v207, 0xffff0000, v102
	v_lshlrev_b32_e32 v208, 16, v103
	v_and_b32_e32 v209, 0xffff0000, v103
	v_lshlrev_b32_e32 v210, 16, v70
	v_and_b32_e32 v211, 0xffff0000, v70
	v_lshlrev_b32_e32 v212, 16, v71
	v_and_b32_e32 v213, 0xffff0000, v71
	v_pk_fma_f32 v[210:211], v[10:11], v[206:207], v[210:211]
	v_pk_fma_f32 v[212:213], v[12:13], v[208:209], v[212:213]
	v_cvt_pk_bf16_f32 v70, v210, v211
	v_cvt_pk_bf16_f32 v71, v212, v213
	v_lshlrev_b32_e32 v206, 16, v104
	v_and_b32_e32 v207, 0xffff0000, v104
	v_lshlrev_b32_e32 v208, 16, v105
	v_and_b32_e32 v209, 0xffff0000, v105
	v_lshlrev_b32_e32 v210, 16, v72
	v_and_b32_e32 v211, 0xffff0000, v72
	v_lshlrev_b32_e32 v212, 16, v73
	v_and_b32_e32 v213, 0xffff0000, v73
	v_pk_fma_f32 v[210:211], v[14:15], v[206:207], v[210:211]
	v_pk_fma_f32 v[212:213], v[16:17], v[208:209], v[212:213]
	v_cvt_pk_bf16_f32 v72, v210, v211
	v_cvt_pk_bf16_f32 v73, v212, v213
	v_lshlrev_b32_e32 v206, 16, v106
	v_and_b32_e32 v207, 0xffff0000, v106
	v_lshlrev_b32_e32 v208, 16, v107
	v_and_b32_e32 v209, 0xffff0000, v107
	v_lshlrev_b32_e32 v210, 16, v74
	v_and_b32_e32 v211, 0xffff0000, v74
	v_lshlrev_b32_e32 v212, 16, v75
	v_and_b32_e32 v213, 0xffff0000, v75
	v_pk_fma_f32 v[210:211], v[18:19], v[206:207], v[210:211]
	v_pk_fma_f32 v[212:213], v[20:21], v[208:209], v[212:213]
	v_cvt_pk_bf16_f32 v74, v210, v211
	v_cvt_pk_bf16_f32 v75, v212, v213
	v_lshlrev_b32_e32 v206, 16, v108
	v_and_b32_e32 v207, 0xffff0000, v108
	v_lshlrev_b32_e32 v208, 16, v109
	v_and_b32_e32 v209, 0xffff0000, v109
	v_lshlrev_b32_e32 v210, 16, v76
	v_and_b32_e32 v211, 0xffff0000, v76
	v_lshlrev_b32_e32 v212, 16, v77
	v_and_b32_e32 v213, 0xffff0000, v77
	v_pk_fma_f32 v[210:211], v[22:23], v[206:207], v[210:211]
	v_pk_fma_f32 v[212:213], v[24:25], v[208:209], v[212:213]
	v_cvt_pk_bf16_f32 v76, v210, v211
	v_cvt_pk_bf16_f32 v77, v212, v213
	v_lshlrev_b32_e32 v206, 16, v110
	v_and_b32_e32 v207, 0xffff0000, v110
	v_lshlrev_b32_e32 v208, 16, v111
	v_and_b32_e32 v209, 0xffff0000, v111
	v_lshlrev_b32_e32 v210, 16, v78
	v_and_b32_e32 v211, 0xffff0000, v78
	v_lshlrev_b32_e32 v212, 16, v79
	v_and_b32_e32 v213, 0xffff0000, v79
	v_pk_fma_f32 v[210:211], v[26:27], v[206:207], v[210:211]
	v_pk_fma_f32 v[212:213], v[28:29], v[208:209], v[212:213]
	v_cvt_pk_bf16_f32 v78, v210, v211
	v_cvt_pk_bf16_f32 v79, v212, v213
	v_lshlrev_b32_e32 v206, 16, v112
	v_and_b32_e32 v207, 0xffff0000, v112
	v_lshlrev_b32_e32 v208, 16, v113
	v_and_b32_e32 v209, 0xffff0000, v113
	v_lshlrev_b32_e32 v210, 16, v80
	v_and_b32_e32 v211, 0xffff0000, v80
	v_lshlrev_b32_e32 v212, 16, v81
	v_and_b32_e32 v213, 0xffff0000, v81
	v_pk_fma_f32 v[210:211], v[30:31], v[206:207], v[210:211]
	v_pk_fma_f32 v[212:213], v[32:33], v[208:209], v[212:213]
	v_cvt_pk_bf16_f32 v80, v210, v211
	v_cvt_pk_bf16_f32 v81, v212, v213
	v_lshlrev_b32_e32 v206, 16, v114
	v_and_b32_e32 v207, 0xffff0000, v114
	v_lshlrev_b32_e32 v208, 16, v115
	v_and_b32_e32 v209, 0xffff0000, v115
	v_lshlrev_b32_e32 v210, 16, v82
	v_and_b32_e32 v211, 0xffff0000, v82
	v_lshlrev_b32_e32 v212, 16, v83
	v_and_b32_e32 v213, 0xffff0000, v83
	v_pk_fma_f32 v[210:211], v[34:35], v[206:207], v[210:211]
	v_pk_fma_f32 v[212:213], v[36:37], v[208:209], v[212:213]
	v_cvt_pk_bf16_f32 v82, v210, v211
	v_cvt_pk_bf16_f32 v83, v212, v213
	v_lshlrev_b32_e32 v206, 16, v116
	v_and_b32_e32 v207, 0xffff0000, v116
	v_lshlrev_b32_e32 v208, 16, v117
	v_and_b32_e32 v209, 0xffff0000, v117
	v_lshlrev_b32_e32 v210, 16, v84
	v_and_b32_e32 v211, 0xffff0000, v84
	v_lshlrev_b32_e32 v212, 16, v85
	v_and_b32_e32 v213, 0xffff0000, v85
; #define LAS __attribute__((address_space(3)))
; __device__ __forceinline__ void branch_phase(LAS unsigned char* lds, const bf16_t* __restrict__ O, const bf16_t* __restrict__ Wb, const bf16_t* __restrict__ Gt, bf16_t* __restrict__ MG, int tg, int wv) {
;     ...
;             for (int kc = 0; kc < 4; ++kc) {
;                 const int c = j * 4 + kc;
;                 if (c + 1 < 16) BR_LOAD(c + 1, (c + 1) & 1);
;                 if (kc == 3) {
;                     const bf16_t* gp = Gt + (size_t)(rt * 128 + wm * 64 + fr) * ZC + j * 1024 + ct * 256 + wn * 64 + 4 * fq;
; #pragma unroll
;                     for (int m = 0; m < 4; ++m)
; #pragma unroll
;                         for (int n = 0; n < 4; ++n) gv[m][n] = *(const u32x2*)(gp + (size_t)m * 16 * ZC + n * 16);
;                 }
;                 LAS const unsigned char* st = lds + (c & 1) * STG;
; #pragma unroll
;                 for (int k = 0; k < 2; ++k) {
;                     __builtin_amdgcn_sched_barrier(0);
;                     bf16x8 af[4], bfr[4];
; #pragma unroll
;                     for (int m = 0; m < 4; ++m) af[m] = *(LAS const bf16x8*)(st + aoff + m * 2048 + k * 1024);
; #pragma unroll
;                     for (int n = 0; n < 4; ++n) bfr[n] = *(LAS const bf16x8*)(st + boff + n * 2048 + k * 1024);
; #pragma unroll
;                     for (int m = 0; m < 4; ++m)
; #pragma unroll
;                         for (int n = 0; n < 4; ++n) acc[m][n] = __builtin_amdgcn_mfma_f32_16x16x32_bf16(bfr[n], af[m], acc[m][n], 0, 0, 0);
;                 }
;                 asm volatile("s_waitcnt vmcnt(0)" ::: "memory"); __syncthreads();
;     ...
; #pragma unroll
;             for (int m = 0; m < 4; ++m)
; #pragma unroll
;                 for (int n = 0; n < 4; ++n) { const u32x2 g = gv[m][n], sp = sum[m][n];
;                     const float s0_ = __builtin_bit_cast(float, sp.x << 16) + acc[m][n][0] * __builtin_bit_cast(float, g.x << 16), s1_ = __builtin_bit_cast(float, sp.x & 0xffff0000u) + acc[m][n][1] * __builtin_bit_cast(float, g.x & 0xffff0000u);
;                     const float s2_ = __builtin_bit_cast(float, sp.y << 16) + acc[m][n][2] * __builtin_bit_cast(float, g.y << 16), s3_ = __builtin_bit_cast(float, sp.y & 0xffff0000u) + acc[m][n][3] * __builtin_bit_cast(float, g.y & 0xffff0000u);
;                     sum[m][n] = (u32x2){cvtpk(s0_, s1_), cvtpk(s2_, s3_)}; }
	v_pk_fma_f32 v[210:211], v[38:39], v[206:207], v[210:211]
	v_pk_fma_f32 v[212:213], v[40:41], v[208:209], v[212:213]
	v_cvt_pk_bf16_f32 v84, v210, v211
	v_cvt_pk_bf16_f32 v85, v212, v213
	v_lshlrev_b32_e32 v206, 16, v118
	v_and_b32_e32 v207, 0xffff0000, v118
	v_lshlrev_b32_e32 v208, 16, v119
	v_and_b32_e32 v209, 0xffff0000, v119
	v_lshlrev_b32_e32 v210, 16, v86
	v_and_b32_e32 v211, 0xffff0000, v86
	v_lshlrev_b32_e32 v212, 16, v87
	v_and_b32_e32 v213, 0xffff0000, v87
	v_pk_fma_f32 v[210:211], v[42:43], v[206:207], v[210:211]
	v_pk_fma_f32 v[212:213], v[44:45], v[208:209], v[212:213]
	v_cvt_pk_bf16_f32 v86, v210, v211
	v_cvt_pk_bf16_f32 v87, v212, v213
	v_lshlrev_b32_e32 v206, 16, v120
	v_and_b32_e32 v207, 0xffff0000, v120
	v_lshlrev_b32_e32 v208, 16, v121
	v_and_b32_e32 v209, 0xffff0000, v121
	v_lshlrev_b32_e32 v210, 16, v88
	v_and_b32_e32 v211, 0xffff0000, v88
	v_lshlrev_b32_e32 v212, 16, v89
	v_and_b32_e32 v213, 0xffff0000, v89
	v_pk_fma_f32 v[210:211], v[46:47], v[206:207], v[210:211]
	v_pk_fma_f32 v[212:213], v[48:49], v[208:209], v[212:213]
	v_cvt_pk_bf16_f32 v88, v210, v211
	v_cvt_pk_bf16_f32 v89, v212, v213
	v_lshlrev_b32_e32 v206, 16, v122
	v_and_b32_e32 v207, 0xffff0000, v122
	v_lshlrev_b32_e32 v208, 16, v123
	v_and_b32_e32 v209, 0xffff0000, v123
	v_lshlrev_b32_e32 v210, 16, v90
	v_and_b32_e32 v211, 0xffff0000, v90
	v_lshlrev_b32_e32 v212, 16, v91
	v_and_b32_e32 v213, 0xffff0000, v91
	v_pk_fma_f32 v[210:211], v[50:51], v[206:207], v[210:211]
	v_pk_fma_f32 v[212:213], v[52:53], v[208:209], v[212:213]
	v_cvt_pk_bf16_f32 v90, v210, v211
	v_cvt_pk_bf16_f32 v91, v212, v213
	v_lshlrev_b32_e32 v206, 16, v124
	v_and_b32_e32 v207, 0xffff0000, v124
	v_lshlrev_b32_e32 v208, 16, v125
	v_and_b32_e32 v209, 0xffff0000, v125
	v_lshlrev_b32_e32 v210, 16, v92
	v_and_b32_e32 v211, 0xffff0000, v92
	v_lshlrev_b32_e32 v212, 16, v93
	v_and_b32_e32 v213, 0xffff0000, v93
	v_pk_fma_f32 v[210:211], v[54:55], v[206:207], v[210:211]
	v_pk_fma_f32 v[212:213], v[56:57], v[208:209], v[212:213]
	v_cvt_pk_bf16_f32 v92, v210, v211
	v_cvt_pk_bf16_f32 v93, v212, v213
	v_lshlrev_b32_e32 v206, 16, v126
	v_and_b32_e32 v207, 0xffff0000, v126
	v_lshlrev_b32_e32 v208, 16, v127
	v_and_b32_e32 v209, 0xffff0000, v127
	v_lshlrev_b32_e32 v210, 16, v94
	v_and_b32_e32 v211, 0xffff0000, v94
	v_lshlrev_b32_e32 v212, 16, v95
	v_and_b32_e32 v213, 0xffff0000, v95
	v_pk_fma_f32 v[210:211], v[58:59], v[206:207], v[210:211]
	v_pk_fma_f32 v[212:213], v[60:61], v[208:209], v[212:213]
	v_cvt_pk_bf16_f32 v94, v210, v211
	v_cvt_pk_bf16_f32 v95, v212, v213
	v_lshlrev_b32_e32 v206, 16, v128
	v_and_b32_e32 v207, 0xffff0000, v128
	v_lshlrev_b32_e32 v208, 16, v129
	v_and_b32_e32 v209, 0xffff0000, v129
	v_lshlrev_b32_e32 v210, 16, v96
	v_and_b32_e32 v211, 0xffff0000, v96
	v_lshlrev_b32_e32 v212, 16, v97
	v_and_b32_e32 v213, 0xffff0000, v97
	v_pk_fma_f32 v[210:211], v[62:63], v[206:207], v[210:211]
	v_pk_fma_f32 v[212:213], v[64:65], v[208:209], v[212:213]
	v_cvt_pk_bf16_f32 v96, v210, v211
	v_cvt_pk_bf16_f32 v97, v212, v213
	s_add_u32 s66, s64, 0x500
	s_addc_u32 s67, s65, 0
	s_add_u32 s70, s68, 0x100100
	s_addc_u32 s71, s69, 0
	s_add_u32 s72, s70, 0x10000
	s_addc_u32 s73, s71, 0
	s_add_i32 m0, s78, 0xc000
	s_nop 0
	global_load_lds_dwordx4 v197, s[66:67]
	s_add_i32 m0, s78, 0xe000
	s_nop 0
	global_load_lds_dwordx4 v198, s[66:67]
	s_add_i32 m0, s78, 0x10000
	s_nop 0
	global_load_lds_dwordx4 v199, s[70:71]
	s_add_i32 m0, s78, 0x12000
	s_nop 0
	global_load_lds_dwordx4 v200, s[70:71]
	s_add_i32 m0, s78, 0x14000
	s_nop 0
	global_load_lds_dwordx4 v199, s[72:73]
	s_add_i32 m0, s78, 0x16000
	s_nop 0
	global_load_lds_dwordx4 v200, s[72:73]
	ds_read_b128 v[130:133], v216 offset:0
	ds_read_b128 v[134:137], v216 offset:2048
	ds_read_b128 v[138:141], v216 offset:4096
	ds_read_b128 v[142:145], v216 offset:6144
	ds_read_b128 v[162:165], v219 offset:0
	ds_read_b128 v[166:169], v219 offset:2048
	ds_read_b128 v[170:173], v219 offset:4096
	ds_read_b128 v[174:177], v219 offset:6144
	ds_read_b128 v[146:149], v216 offset:1024
	ds_read_b128 v[150:153], v216 offset:3072
	ds_read_b128 v[154:157], v216 offset:5120
	ds_read_b128 v[158:161], v216 offset:7168
	ds_read_b128 v[178:181], v219 offset:1024
	ds_read_b128 v[182:185], v219 offset:3072
	ds_read_b128 v[186:189], v219 offset:5120
	ds_read_b128 v[190:193], v219 offset:7168
	s_waitcnt lgkmcnt(8)
	v_mfma_f32_16x16x32_bf16 v[2:5], v[162:165], v[130:133], 0
	v_mfma_f32_16x16x32_bf16 v[6:9], v[166:169], v[130:133], 0
	v_mfma_f32_16x16x32_bf16 v[10:13], v[170:173], v[130:133], 0
	v_mfma_f32_16x16x32_bf16 v[14:17], v[174:177], v[130:133], 0
	v_mfma_f32_16x16x32_bf16 v[18:21], v[162:165], v[134:137], 0
	v_mfma_f32_16x16x32_bf16 v[22:25], v[166:169], v[134:137], 0
	v_mfma_f32_16x16x32_bf16 v[26:29], v[170:173], v[134:137], 0
	v_mfma_f32_16x16x32_bf16 v[30:33], v[174:177], v[134:137], 0
	v_mfma_f32_16x16x32_bf16 v[34:37], v[162:165], v[138:141], 0
	v_mfma_f32_16x16x32_bf16 v[38:41], v[166:169], v[138:141], 0
	v_mfma_f32_16x16x32_bf16 v[42:45], v[170:173], v[138:141], 0
	v_mfma_f32_16x16x32_bf16 v[46:49], v[174:177], v[138:141], 0
	v_mfma_f32_16x16x32_bf16 v[50:53], v[162:165], v[142:145], 0
	v_mfma_f32_16x16x32_bf16 v[54:57], v[166:169], v[142:145], 0
	v_mfma_f32_16x16x32_bf16 v[58:61], v[170:173], v[142:145], 0
	v_mfma_f32_16x16x32_bf16 v[62:65], v[174:177], v[142:145], 0
	s_waitcnt lgkmcnt(0)
	v_mfma_f32_16x16x32_bf16 v[2:5], v[178:181], v[146:149], v[2:5]
	v_mfma_f32_16x16x32_bf16 v[6:9], v[182:185], v[146:149], v[6:9]
	v_mfma_f32_16x16x32_bf16 v[10:13], v[186:189], v[146:149], v[10:13]
	v_mfma_f32_16x16x32_bf16 v[14:17], v[190:193], v[146:149], v[14:17]
	v_mfma_f32_16x16x32_bf16 v[18:21], v[178:181], v[150:153], v[18:21]
	v_mfma_f32_16x16x32_bf16 v[22:25], v[182:185], v[150:153], v[22:25]
	v_mfma_f32_16x16x32_bf16 v[26:29], v[186:189], v[150:153], v[26:29]
	v_mfma_f32_16x16x32_bf16 v[30:33], v[190:193], v[150:153], v[30:33]
	v_mfma_f32_16x16x32_bf16 v[34:37], v[178:181], v[154:157], v[34:37]
	v_mfma_f32_16x16x32_bf16 v[38:41], v[182:185], v[154:157], v[38:41]
	v_mfma_f32_16x16x32_bf16 v[42:45], v[186:189], v[154:157], v[42:45]
	v_mfma_f32_16x16x32_bf16 v[46:49], v[190:193], v[154:157], v[46:49]
	v_mfma_f32_16x16x32_bf16 v[50:53], v[178:181], v[158:161], v[50:53]
	v_mfma_f32_16x16x32_bf16 v[54:57], v[182:185], v[158:161], v[54:57]
	v_mfma_f32_16x16x32_bf16 v[58:61], v[186:189], v[158:161], v[58:61]
	v_mfma_f32_16x16x32_bf16 v[62:65], v[190:193], v[158:161], v[62:65]
	s_waitcnt vmcnt(6)
	s_barrier
; #define LAS __attribute__((address_space(3)))
; __device__ __forceinline__ void branch_phase(LAS unsigned char* lds, const bf16_t* __restrict__ O, const bf16_t* __restrict__ Wb, const bf16_t* __restrict__ Gt, bf16_t* __restrict__ MG, int tg, int wv) {
;     ...
;         BR_LOAD(0, 0);
;         asm volatile("s_waitcnt vmcnt(0)" ::: "memory"); __syncthreads();
;         for (int j = 0; j < 4; ++j) {
;             u32x2 gv[4][4];
;             f32x4 acc[4][4];
; #pragma unroll
;             for (int m = 0; m < 4; ++m)
; #pragma unroll
;                 for (int n = 0; n < 4; ++n) acc[m][n] = (f32x4){0.f, 0.f, 0.f, 0.f};
;             for (int kc = 0; kc < 4; ++kc) {
;                 const int c = j * 4 + kc;
;                 if (c + 1 < 16) BR_LOAD(c + 1, (c + 1) & 1);
;                 if (kc == 3) {
;                     const bf16_t* gp = Gt + (size_t)(rt * 128 + wm * 64 + fr) * ZC + j * 1024 + ct * 256 + wn * 64 + 4 * fq;
; #pragma unroll
;                     for (int m = 0; m < 4; ++m)
; #pragma unroll
;                         for (int n = 0; n < 4; ++n) gv[m][n] = *(const u32x2*)(gp + (size_t)m * 16 * ZC + n * 16);
;                 }
;                 LAS const unsigned char* st = lds + (c & 1) * STG;
; #pragma unroll
;                 for (int k = 0; k < 2; ++k) {
;                     __builtin_amdgcn_sched_barrier(0);
;                     bf16x8 af[4], bfr[4];
; #pragma unroll
;                     for (int m = 0; m < 4; ++m) af[m] = *(LAS const bf16x8*)(st + aoff + m * 2048 + k * 1024);
; #pragma unroll
;                     for (int n = 0; n < 4; ++n) bfr[n] = *(LAS const bf16x8*)(st + boff + n * 2048 + k * 1024);
; #pragma unroll
;                     for (int m = 0; m < 4; ++m)
; #pragma unroll
;                         for (int n = 0; n < 4; ++n) acc[m][n] = __builtin_amdgcn_mfma_f32_16x16x32_bf16(bfr[n], af[m], acc[m][n], 0, 0, 0);
;                 }
;                 asm volatile("s_waitcnt vmcnt(0)" ::: "memory"); __syncthreads();
	s_add_u32 s66, s64, 0x580
	s_addc_u32 s67, s65, 0
	s_add_u32 s70, s68, 0x100180
	s_addc_u32 s71, s69, 0
	s_add_u32 s72, s70, 0x10000
	s_addc_u32 s73, s71, 0
	s_add_i32 m0, s78, 0x18000
	s_nop 0
	global_load_lds_dwordx4 v197, s[66:67]
	s_add_i32 m0, s78, 0x1a000
	s_nop 0
	global_load_lds_dwordx4 v198, s[66:67]
	s_add_i32 m0, s78, 0x1c000
	s_nop 0
	global_load_lds_dwordx4 v199, s[70:71]
	s_add_i32 m0, s78, 0x1e000
	s_nop 0
	global_load_lds_dwordx4 v200, s[70:71]
	s_add_i32 m0, s78, 0x20800
	s_nop 0
	global_load_lds_dwordx4 v199, s[72:73]
	s_add_i32 m0, s78, 0x22800
	s_nop 0
	global_load_lds_dwordx4 v200, s[72:73]
	s_add_u32 s80, s74, 0x1000
	s_addc_u32 s81, s75, 0
	global_load_dwordx2 v[98:99], v204, s[80:81] offset:0
	global_load_dwordx2 v[100:101], v204, s[80:81] offset:32
	global_load_dwordx2 v[102:103], v204, s[80:81] offset:64
	global_load_dwordx2 v[104:105], v204, s[80:81] offset:96
	s_add_u32 s80, s80, 0x20000
	s_addc_u32 s81, s81, 0
	global_load_dwordx2 v[106:107], v204, s[80:81] offset:0
	global_load_dwordx2 v[108:109], v204, s[80:81] offset:32
	global_load_dwordx2 v[110:111], v204, s[80:81] offset:64
	global_load_dwordx2 v[112:113], v204, s[80:81] offset:96
	s_add_u32 s80, s80, 0x20000
	s_addc_u32 s81, s81, 0
	global_load_dwordx2 v[114:115], v204, s[80:81] offset:0
	global_load_dwordx2 v[116:117], v204, s[80:81] offset:32
	global_load_dwordx2 v[118:119], v204, s[80:81] offset:64
	global_load_dwordx2 v[120:121], v204, s[80:81] offset:96
	s_add_u32 s80, s80, 0x20000
	s_addc_u32 s81, s81, 0
	global_load_dwordx2 v[122:123], v204, s[80:81] offset:0
	global_load_dwordx2 v[124:125], v204, s[80:81] offset:32
	global_load_dwordx2 v[126:127], v204, s[80:81] offset:64
	global_load_dwordx2 v[128:129], v204, s[80:81] offset:96
	ds_read_b128 v[130:133], v214 offset:0
	ds_read_b128 v[134:137], v214 offset:2048
	ds_read_b128 v[138:141], v214 offset:4096
	ds_read_b128 v[142:145], v214 offset:6144
	ds_read_b128 v[162:165], v217 offset:0
	ds_read_b128 v[166:169], v217 offset:2048
	ds_read_b128 v[170:173], v217 offset:4096
	ds_read_b128 v[174:177], v217 offset:6144
	ds_read_b128 v[146:149], v214 offset:1024
	ds_read_b128 v[150:153], v214 offset:3072
	ds_read_b128 v[154:157], v214 offset:5120
	ds_read_b128 v[158:161], v214 offset:7168
	ds_read_b128 v[178:181], v217 offset:1024
	ds_read_b128 v[182:185], v217 offset:3072
	ds_read_b128 v[186:189], v217 offset:5120
	ds_read_b128 v[190:193], v217 offset:7168
	s_waitcnt lgkmcnt(8)
	v_mfma_f32_16x16x32_bf16 v[2:5], v[162:165], v[130:133], v[2:5]
	v_mfma_f32_16x16x32_bf16 v[6:9], v[166:169], v[130:133], v[6:9]
	v_mfma_f32_16x16x32_bf16 v[10:13], v[170:173], v[130:133], v[10:13]
	v_mfma_f32_16x16x32_bf16 v[14:17], v[174:177], v[130:133], v[14:17]
	v_mfma_f32_16x16x32_bf16 v[18:21], v[162:165], v[134:137], v[18:21]
	v_mfma_f32_16x16x32_bf16 v[22:25], v[166:169], v[134:137], v[22:25]
	v_mfma_f32_16x16x32_bf16 v[26:29], v[170:173], v[134:137], v[26:29]
	v_mfma_f32_16x16x32_bf16 v[30:33], v[174:177], v[134:137], v[30:33]
	v_mfma_f32_16x16x32_bf16 v[34:37], v[162:165], v[138:141], v[34:37]
	v_mfma_f32_16x16x32_bf16 v[38:41], v[166:169], v[138:141], v[38:41]
	v_mfma_f32_16x16x32_bf16 v[42:45], v[170:173], v[138:141], v[42:45]
	v_mfma_f32_16x16x32_bf16 v[46:49], v[174:177], v[138:141], v[46:49]
	v_mfma_f32_16x16x32_bf16 v[50:53], v[162:165], v[142:145], v[50:53]
	v_mfma_f32_16x16x32_bf16 v[54:57], v[166:169], v[142:145], v[54:57]
	v_mfma_f32_16x16x32_bf16 v[58:61], v[170:173], v[142:145], v[58:61]
	v_mfma_f32_16x16x32_bf16 v[62:65], v[174:177], v[142:145], v[62:65]
	s_waitcnt lgkmcnt(0)
	v_mfma_f32_16x16x32_bf16 v[2:5], v[178:181], v[146:149], v[2:5]
	v_mfma_f32_16x16x32_bf16 v[6:9], v[182:185], v[146:149], v[6:9]
	v_mfma_f32_16x16x32_bf16 v[10:13], v[186:189], v[146:149], v[10:13]
	v_mfma_f32_16x16x32_bf16 v[14:17], v[190:193], v[146:149], v[14:17]
	v_mfma_f32_16x16x32_bf16 v[18:21], v[178:181], v[150:153], v[18:21]
	v_mfma_f32_16x16x32_bf16 v[22:25], v[182:185], v[150:153], v[22:25]
	v_mfma_f32_16x16x32_bf16 v[26:29], v[186:189], v[150:153], v[26:29]
	v_mfma_f32_16x16x32_bf16 v[30:33], v[190:193], v[150:153], v[30:33]
	v_mfma_f32_16x16x32_bf16 v[34:37], v[178:181], v[154:157], v[34:37]
	v_mfma_f32_16x16x32_bf16 v[38:41], v[182:185], v[154:157], v[38:41]
	v_mfma_f32_16x16x32_bf16 v[42:45], v[186:189], v[154:157], v[42:45]
	v_mfma_f32_16x16x32_bf16 v[46:49], v[190:193], v[154:157], v[46:49]
	v_mfma_f32_16x16x32_bf16 v[50:53], v[178:181], v[158:161], v[50:53]
	v_mfma_f32_16x16x32_bf16 v[54:57], v[182:185], v[158:161], v[54:57]
	v_mfma_f32_16x16x32_bf16 v[58:61], v[186:189], v[158:161], v[58:61]
	v_mfma_f32_16x16x32_bf16 v[62:65], v[190:193], v[158:161], v[62:65]
	s_waitcnt vmcnt(22)
	s_barrier
; #define LAS __attribute__((address_space(3)))
; __device__ __forceinline__ void branch_phase(LAS unsigned char* lds, const bf16_t* __restrict__ O, const bf16_t* __restrict__ Wb, const bf16_t* __restrict__ Gt, bf16_t* __restrict__ MG, int tg, int wv) {
;     ...
;         BR_LOAD(0, 0);
;         asm volatile("s_waitcnt vmcnt(0)" ::: "memory"); __syncthreads();
;         for (int j = 0; j < 4; ++j) {
;             u32x2 gv[4][4];
;             f32x4 acc[4][4];
; #pragma unroll
;             for (int m = 0; m < 4; ++m)
; #pragma unroll
;                 for (int n = 0; n < 4; ++n) acc[m][n] = (f32x4){0.f, 0.f, 0.f, 0.f};
;             for (int kc = 0; kc < 4; ++kc) {
;                 const int c = j * 4 + kc;
;                 if (c + 1 < 16) BR_LOAD(c + 1, (c + 1) & 1);
;                 if (kc == 3) {
;                     const bf16_t* gp = Gt + (size_t)(rt * 128 + wm * 64 + fr) * ZC + j * 1024 + ct * 256 + wn * 64 + 4 * fq;
; #pragma unroll
;                     for (int m = 0; m < 4; ++m)
; #pragma unroll
;                         for (int n = 0; n < 4; ++n) gv[m][n] = *(const u32x2*)(gp + (size_t)m * 16 * ZC + n * 16);
;                 }
;                 LAS const unsigned char* st = lds + (c & 1) * STG;
; #pragma unroll
;                 for (int k = 0; k < 2; ++k) {
;                     __builtin_amdgcn_sched_barrier(0);
;                     bf16x8 af[4], bfr[4];
; #pragma unroll
;                     for (int m = 0; m < 4; ++m) af[m] = *(LAS const bf16x8*)(st + aoff + m * 2048 + k * 1024);
; #pragma unroll
;                     for (int n = 0; n < 4; ++n) bfr[n] = *(LAS const bf16x8*)(st + boff + n * 2048 + k * 1024);
; #pragma unroll
;                     for (int m = 0; m < 4; ++m)
; #pragma unroll
;                         for (int n = 0; n < 4; ++n) acc[m][n] = __builtin_amdgcn_mfma_f32_16x16x32_bf16(bfr[n], af[m], acc[m][n], 0, 0, 0);
;                 }
;                 asm volatile("s_waitcnt vmcnt(0)" ::: "memory"); __syncthreads();
	s_add_u32 s66, s64, 0x600
	s_addc_u32 s67, s65, 0
	s_add_u32 s70, s68, 0x180000
	s_addc_u32 s71, s69, 0
	s_add_u32 s72, s70, 0x10000
	s_addc_u32 s73, s71, 0
	s_add_i32 m0, s78, 0x0
	s_nop 0
	global_load_lds_dwordx4 v197, s[66:67]
	s_add_i32 m0, s78, 0x2000
	s_nop 0
	global_load_lds_dwordx4 v198, s[66:67]
	s_add_i32 m0, s78, 0x4000
	s_nop 0
	global_load_lds_dwordx4 v199, s[70:71]
	s_add_i32 m0, s78, 0x6000
	s_nop 0
	global_load_lds_dwordx4 v200, s[70:71]
	s_add_i32 m0, s78, 0x8000
	s_nop 0
	global_load_lds_dwordx4 v199, s[72:73]
	s_add_i32 m0, s78, 0xa000
	s_nop 0
	global_load_lds_dwordx4 v200, s[72:73]
	ds_read_b128 v[130:133], v215 offset:0
	ds_read_b128 v[134:137], v215 offset:2048
	ds_read_b128 v[138:141], v215 offset:4096
	ds_read_b128 v[142:145], v215 offset:6144
	ds_read_b128 v[162:165], v218 offset:0
	ds_read_b128 v[166:169], v218 offset:2048
	ds_read_b128 v[170:173], v218 offset:4096
	ds_read_b128 v[174:177], v218 offset:6144
	ds_read_b128 v[146:149], v215 offset:1024
	ds_read_b128 v[150:153], v215 offset:3072
	ds_read_b128 v[154:157], v215 offset:5120
	ds_read_b128 v[158:161], v215 offset:7168
	ds_read_b128 v[178:181], v218 offset:1024
	ds_read_b128 v[182:185], v218 offset:3072
	ds_read_b128 v[186:189], v218 offset:5120
	ds_read_b128 v[190:193], v218 offset:7168
	s_waitcnt lgkmcnt(8)
	v_mfma_f32_16x16x32_bf16 v[2:5], v[162:165], v[130:133], v[2:5]
	v_mfma_f32_16x16x32_bf16 v[6:9], v[166:169], v[130:133], v[6:9]
	v_mfma_f32_16x16x32_bf16 v[10:13], v[170:173], v[130:133], v[10:13]
	v_mfma_f32_16x16x32_bf16 v[14:17], v[174:177], v[130:133], v[14:17]
	v_mfma_f32_16x16x32_bf16 v[18:21], v[162:165], v[134:137], v[18:21]
	v_mfma_f32_16x16x32_bf16 v[22:25], v[166:169], v[134:137], v[22:25]
	v_mfma_f32_16x16x32_bf16 v[26:29], v[170:173], v[134:137], v[26:29]
	v_mfma_f32_16x16x32_bf16 v[30:33], v[174:177], v[134:137], v[30:33]
	v_mfma_f32_16x16x32_bf16 v[34:37], v[162:165], v[138:141], v[34:37]
	v_mfma_f32_16x16x32_bf16 v[38:41], v[166:169], v[138:141], v[38:41]
	v_mfma_f32_16x16x32_bf16 v[42:45], v[170:173], v[138:141], v[42:45]
	v_mfma_f32_16x16x32_bf16 v[46:49], v[174:177], v[138:141], v[46:49]
	v_mfma_f32_16x16x32_bf16 v[50:53], v[162:165], v[142:145], v[50:53]
	v_mfma_f32_16x16x32_bf16 v[54:57], v[166:169], v[142:145], v[54:57]
	v_mfma_f32_16x16x32_bf16 v[58:61], v[170:173], v[142:145], v[58:61]
	v_mfma_f32_16x16x32_bf16 v[62:65], v[174:177], v[142:145], v[62:65]
	s_waitcnt lgkmcnt(0)
	v_mfma_f32_16x16x32_bf16 v[2:5], v[178:181], v[146:149], v[2:5]
	v_mfma_f32_16x16x32_bf16 v[6:9], v[182:185], v[146:149], v[6:9]
	v_mfma_f32_16x16x32_bf16 v[10:13], v[186:189], v[146:149], v[10:13]
	v_mfma_f32_16x16x32_bf16 v[14:17], v[190:193], v[146:149], v[14:17]
	v_mfma_f32_16x16x32_bf16 v[18:21], v[178:181], v[150:153], v[18:21]
	v_mfma_f32_16x16x32_bf16 v[22:25], v[182:185], v[150:153], v[22:25]
	v_mfma_f32_16x16x32_bf16 v[26:29], v[186:189], v[150:153], v[26:29]
	v_mfma_f32_16x16x32_bf16 v[30:33], v[190:193], v[150:153], v[30:33]
	v_mfma_f32_16x16x32_bf16 v[34:37], v[178:181], v[154:157], v[34:37]
	v_mfma_f32_16x16x32_bf16 v[38:41], v[182:185], v[154:157], v[38:41]
	v_mfma_f32_16x16x32_bf16 v[42:45], v[186:189], v[154:157], v[42:45]
	v_mfma_f32_16x16x32_bf16 v[46:49], v[190:193], v[154:157], v[46:49]
	v_mfma_f32_16x16x32_bf16 v[50:53], v[178:181], v[158:161], v[50:53]
	v_mfma_f32_16x16x32_bf16 v[54:57], v[182:185], v[158:161], v[54:57]
	v_mfma_f32_16x16x32_bf16 v[58:61], v[186:189], v[158:161], v[58:61]
	v_mfma_f32_16x16x32_bf16 v[62:65], v[190:193], v[158:161], v[62:65]
	s_waitcnt vmcnt(22)
	s_barrier
	s_add_u32 s66, s64, 0x680
	s_addc_u32 s67, s65, 0
	s_add_u32 s70, s68, 0x180080
	s_addc_u32 s71, s69, 0
	s_add_u32 s72, s70, 0x10000
	s_addc_u32 s73, s71, 0
	s_add_i32 m0, s78, 0xc000
	s_nop 0
	global_load_lds_dwordx4 v197, s[66:67]
	s_add_i32 m0, s78, 0xe000
	s_nop 0
	global_load_lds_dwordx4 v198, s[66:67]
	s_add_i32 m0, s78, 0x10000
	s_nop 0
	global_load_lds_dwordx4 v199, s[70:71]
	s_add_i32 m0, s78, 0x12000
	s_nop 0
	global_load_lds_dwordx4 v200, s[70:71]
	s_add_i32 m0, s78, 0x14000
	s_nop 0
	global_load_lds_dwordx4 v199, s[72:73]
	s_add_i32 m0, s78, 0x16000
	s_nop 0
	global_load_lds_dwordx4 v200, s[72:73]
	ds_read_b128 v[130:133], v216 offset:0
	ds_read_b128 v[134:137], v216 offset:2048
	ds_read_b128 v[138:141], v216 offset:4096
	ds_read_b128 v[142:145], v216 offset:6144
	ds_read_b128 v[162:165], v219 offset:0
	ds_read_b128 v[166:169], v219 offset:2048
	ds_read_b128 v[170:173], v219 offset:4096
	ds_read_b128 v[174:177], v219 offset:6144
	ds_read_b128 v[146:149], v216 offset:1024
	ds_read_b128 v[150:153], v216 offset:3072
	ds_read_b128 v[154:157], v216 offset:5120
	ds_read_b128 v[158:161], v216 offset:7168
	ds_read_b128 v[178:181], v219 offset:1024
	ds_read_b128 v[182:185], v219 offset:3072
	ds_read_b128 v[186:189], v219 offset:5120
	ds_read_b128 v[190:193], v219 offset:7168
	s_waitcnt lgkmcnt(8)
	v_mfma_f32_16x16x32_bf16 v[2:5], v[162:165], v[130:133], v[2:5]
	v_mfma_f32_16x16x32_bf16 v[6:9], v[166:169], v[130:133], v[6:9]
	v_mfma_f32_16x16x32_bf16 v[10:13], v[170:173], v[130:133], v[10:13]
	v_mfma_f32_16x16x32_bf16 v[14:17], v[174:177], v[130:133], v[14:17]
	v_mfma_f32_16x16x32_bf16 v[18:21], v[162:165], v[134:137], v[18:21]
	v_mfma_f32_16x16x32_bf16 v[22:25], v[166:169], v[134:137], v[22:25]
	v_mfma_f32_16x16x32_bf16 v[26:29], v[170:173], v[134:137], v[26:29]
	v_mfma_f32_16x16x32_bf16 v[30:33], v[174:177], v[134:137], v[30:33]
	v_mfma_f32_16x16x32_bf16 v[34:37], v[162:165], v[138:141], v[34:37]
	v_mfma_f32_16x16x32_bf16 v[38:41], v[166:169], v[138:141], v[38:41]
	v_mfma_f32_16x16x32_bf16 v[42:45], v[170:173], v[138:141], v[42:45]
	v_mfma_f32_16x16x32_bf16 v[46:49], v[174:177], v[138:141], v[46:49]
	v_mfma_f32_16x16x32_bf16 v[50:53], v[162:165], v[142:145], v[50:53]
	v_mfma_f32_16x16x32_bf16 v[54:57], v[166:169], v[142:145], v[54:57]
	v_mfma_f32_16x16x32_bf16 v[58:61], v[170:173], v[142:145], v[58:61]
	v_mfma_f32_16x16x32_bf16 v[62:65], v[174:177], v[142:145], v[62:65]
	s_waitcnt lgkmcnt(0)
; __device__ __forceinline__ unsigned cvtpk(float lo, float hi) { f32x2 v = {lo, hi}; bf16x2_t b = __builtin_convertvector(v, bf16x2_t); return __builtin_bit_cast(unsigned, b); }
; __device__ __forceinline__ void branch_phase(LAS unsigned char* lds, const bf16_t* __restrict__ O, const bf16_t* __restrict__ Wb, const bf16_t* __restrict__ Gt, bf16_t* __restrict__ MG, int tg, int wv) {
;     ...
; #pragma unroll
;                     for (int m = 0; m < 4; ++m)
; #pragma unroll
;                         for (int n = 0; n < 4; ++n) acc[m][n] = __builtin_amdgcn_mfma_f32_16x16x32_bf16(bfr[n], af[m], acc[m][n], 0, 0, 0);
;                 }
;                 asm volatile("s_waitcnt vmcnt(0)" ::: "memory"); __syncthreads();
;             }
; #pragma unroll
;             for (int m = 0; m < 4; ++m)
; #pragma unroll
;                 for (int n = 0; n < 4; ++n) { const u32x2 g = gv[m][n], sp = sum[m][n];
;                     const float s0_ = __builtin_bit_cast(float, sp.x << 16) + acc[m][n][0] * __builtin_bit_cast(float, g.x << 16), s1_ = __builtin_bit_cast(float, sp.x & 0xffff0000u) + acc[m][n][1] * __builtin_bit_cast(float, g.x & 0xffff0000u);
;                     const float s2_ = __builtin_bit_cast(float, sp.y << 16) + acc[m][n][2] * __builtin_bit_cast(float, g.y << 16), s3_ = __builtin_bit_cast(float, sp.y & 0xffff0000u) + acc[m][n][3] * __builtin_bit_cast(float, g.y & 0xffff0000u);
;                     sum[m][n] = (u32x2){cvtpk(s0_, s1_), cvtpk(s2_, s3_)}; }
	v_mfma_f32_16x16x32_bf16 v[2:5], v[178:181], v[146:149], v[2:5]
	v_mfma_f32_16x16x32_bf16 v[6:9], v[182:185], v[146:149], v[6:9]
	v_mfma_f32_16x16x32_bf16 v[10:13], v[186:189], v[146:149], v[10:13]
	v_mfma_f32_16x16x32_bf16 v[14:17], v[190:193], v[146:149], v[14:17]
	v_mfma_f32_16x16x32_bf16 v[18:21], v[178:181], v[150:153], v[18:21]
	v_mfma_f32_16x16x32_bf16 v[22:25], v[182:185], v[150:153], v[22:25]
	v_mfma_f32_16x16x32_bf16 v[26:29], v[186:189], v[150:153], v[26:29]
	v_mfma_f32_16x16x32_bf16 v[30:33], v[190:193], v[150:153], v[30:33]
	v_mfma_f32_16x16x32_bf16 v[34:37], v[178:181], v[154:157], v[34:37]
	v_mfma_f32_16x16x32_bf16 v[38:41], v[182:185], v[154:157], v[38:41]
	v_mfma_f32_16x16x32_bf16 v[42:45], v[186:189], v[154:157], v[42:45]
	v_mfma_f32_16x16x32_bf16 v[46:49], v[190:193], v[154:157], v[46:49]
	v_mfma_f32_16x16x32_bf16 v[50:53], v[178:181], v[158:161], v[50:53]
	v_mfma_f32_16x16x32_bf16 v[54:57], v[182:185], v[158:161], v[54:57]
	v_mfma_f32_16x16x32_bf16 v[58:61], v[186:189], v[158:161], v[58:61]
	v_mfma_f32_16x16x32_bf16 v[62:65], v[190:193], v[158:161], v[62:65]
	s_waitcnt vmcnt(6)
	s_barrier
	s_nop 7
	v_lshlrev_b32_e32 v206, 16, v98
	v_and_b32_e32 v207, 0xffff0000, v98
	v_lshlrev_b32_e32 v208, 16, v99
	v_and_b32_e32 v209, 0xffff0000, v99
	v_lshlrev_b32_e32 v210, 16, v66
	v_and_b32_e32 v211, 0xffff0000, v66
	v_lshlrev_b32_e32 v212, 16, v67
	v_and_b32_e32 v213, 0xffff0000, v67
	v_pk_fma_f32 v[210:211], v[2:3], v[206:207], v[210:211]
	v_pk_fma_f32 v[212:213], v[4:5], v[208:209], v[212:213]
	v_cvt_pk_bf16_f32 v66, v210, v211
	v_cvt_pk_bf16_f32 v67, v212, v213
	v_lshlrev_b32_e32 v206, 16, v100
	v_and_b32_e32 v207, 0xffff0000, v100
	v_lshlrev_b32_e32 v208, 16, v101
	v_and_b32_e32 v209, 0xffff0000, v101
	v_lshlrev_b32_e32 v210, 16, v68
	v_and_b32_e32 v211, 0xffff0000, v68
	v_lshlrev_b32_e32 v212, 16, v69
	v_and_b32_e32 v213, 0xffff0000, v69
	v_pk_fma_f32 v[210:211], v[6:7], v[206:207], v[210:211]
	v_pk_fma_f32 v[212:213], v[8:9], v[208:209], v[212:213]
	v_cvt_pk_bf16_f32 v68, v210, v211
	v_cvt_pk_bf16_f32 v69, v212, v213
	v_lshlrev_b32_e32 v206, 16, v102
	v_and_b32_e32 v207, 0xffff0000, v102
	v_lshlrev_b32_e32 v208, 16, v103
	v_and_b32_e32 v209, 0xffff0000, v103
	v_lshlrev_b32_e32 v210, 16, v70
	v_and_b32_e32 v211, 0xffff0000, v70
	v_lshlrev_b32_e32 v212, 16, v71
	v_and_b32_e32 v213, 0xffff0000, v71
	v_pk_fma_f32 v[210:211], v[10:11], v[206:207], v[210:211]
	v_pk_fma_f32 v[212:213], v[12:13], v[208:209], v[212:213]
	v_cvt_pk_bf16_f32 v70, v210, v211
	v_cvt_pk_bf16_f32 v71, v212, v213
	v_lshlrev_b32_e32 v206, 16, v104
	v_and_b32_e32 v207, 0xffff0000, v104
	v_lshlrev_b32_e32 v208, 16, v105
	v_and_b32_e32 v209, 0xffff0000, v105
	v_lshlrev_b32_e32 v210, 16, v72
	v_and_b32_e32 v211, 0xffff0000, v72
	v_lshlrev_b32_e32 v212, 16, v73
	v_and_b32_e32 v213, 0xffff0000, v73
	v_pk_fma_f32 v[210:211], v[14:15], v[206:207], v[210:211]
	v_pk_fma_f32 v[212:213], v[16:17], v[208:209], v[212:213]
	v_cvt_pk_bf16_f32 v72, v210, v211
	v_cvt_pk_bf16_f32 v73, v212, v213
	v_lshlrev_b32_e32 v206, 16, v106
	v_and_b32_e32 v207, 0xffff0000, v106
	v_lshlrev_b32_e32 v208, 16, v107
	v_and_b32_e32 v209, 0xffff0000, v107
	v_lshlrev_b32_e32 v210, 16, v74
	v_and_b32_e32 v211, 0xffff0000, v74
	v_lshlrev_b32_e32 v212, 16, v75
	v_and_b32_e32 v213, 0xffff0000, v75
	v_pk_fma_f32 v[210:211], v[18:19], v[206:207], v[210:211]
	v_pk_fma_f32 v[212:213], v[20:21], v[208:209], v[212:213]
	v_cvt_pk_bf16_f32 v74, v210, v211
	v_cvt_pk_bf16_f32 v75, v212, v213
	v_lshlrev_b32_e32 v206, 16, v108
	v_and_b32_e32 v207, 0xffff0000, v108
	v_lshlrev_b32_e32 v208, 16, v109
	v_and_b32_e32 v209, 0xffff0000, v109
	v_lshlrev_b32_e32 v210, 16, v76
	v_and_b32_e32 v211, 0xffff0000, v76
	v_lshlrev_b32_e32 v212, 16, v77
	v_and_b32_e32 v213, 0xffff0000, v77
	v_pk_fma_f32 v[210:211], v[22:23], v[206:207], v[210:211]
	v_pk_fma_f32 v[212:213], v[24:25], v[208:209], v[212:213]
	v_cvt_pk_bf16_f32 v76, v210, v211
	v_cvt_pk_bf16_f32 v77, v212, v213
	v_lshlrev_b32_e32 v206, 16, v110
	v_and_b32_e32 v207, 0xffff0000, v110
	v_lshlrev_b32_e32 v208, 16, v111
	v_and_b32_e32 v209, 0xffff0000, v111
	v_lshlrev_b32_e32 v210, 16, v78
	v_and_b32_e32 v211, 0xffff0000, v78
	v_lshlrev_b32_e32 v212, 16, v79
	v_and_b32_e32 v213, 0xffff0000, v79
	v_pk_fma_f32 v[210:211], v[26:27], v[206:207], v[210:211]
	v_pk_fma_f32 v[212:213], v[28:29], v[208:209], v[212:213]
	v_cvt_pk_bf16_f32 v78, v210, v211
	v_cvt_pk_bf16_f32 v79, v212, v213
	v_lshlrev_b32_e32 v206, 16, v112
	v_and_b32_e32 v207, 0xffff0000, v112
	v_lshlrev_b32_e32 v208, 16, v113
	v_and_b32_e32 v209, 0xffff0000, v113
	v_lshlrev_b32_e32 v210, 16, v80
	v_and_b32_e32 v211, 0xffff0000, v80
	v_lshlrev_b32_e32 v212, 16, v81
	v_and_b32_e32 v213, 0xffff0000, v81
	v_pk_fma_f32 v[210:211], v[30:31], v[206:207], v[210:211]
	v_pk_fma_f32 v[212:213], v[32:33], v[208:209], v[212:213]
	v_cvt_pk_bf16_f32 v80, v210, v211
	v_cvt_pk_bf16_f32 v81, v212, v213
	v_lshlrev_b32_e32 v206, 16, v114
	v_and_b32_e32 v207, 0xffff0000, v114
	v_lshlrev_b32_e32 v208, 16, v115
	v_and_b32_e32 v209, 0xffff0000, v115
	v_lshlrev_b32_e32 v210, 16, v82
	v_and_b32_e32 v211, 0xffff0000, v82
	v_lshlrev_b32_e32 v212, 16, v83
	v_and_b32_e32 v213, 0xffff0000, v83
	v_pk_fma_f32 v[210:211], v[34:35], v[206:207], v[210:211]
	v_pk_fma_f32 v[212:213], v[36:37], v[208:209], v[212:213]
	v_cvt_pk_bf16_f32 v82, v210, v211
	v_cvt_pk_bf16_f32 v83, v212, v213
	v_lshlrev_b32_e32 v206, 16, v116
	v_and_b32_e32 v207, 0xffff0000, v116
	v_lshlrev_b32_e32 v208, 16, v117
	v_and_b32_e32 v209, 0xffff0000, v117
	v_lshlrev_b32_e32 v210, 16, v84
	v_and_b32_e32 v211, 0xffff0000, v84
	v_lshlrev_b32_e32 v212, 16, v85
	v_and_b32_e32 v213, 0xffff0000, v85
; __device__ __forceinline__ void branch_phase(LAS unsigned char* lds, const bf16_t* __restrict__ O, const bf16_t* __restrict__ Wb, const bf16_t* __restrict__ Gt, bf16_t* __restrict__ MG, int tg, int wv) {
;     ...
;         BR_LOAD(0, 0);
;         asm volatile("s_waitcnt vmcnt(0)" ::: "memory"); __syncthreads();
;         for (int j = 0; j < 4; ++j) {
;             u32x2 gv[4][4];
;             f32x4 acc[4][4];
; #pragma unroll
;             for (int m = 0; m < 4; ++m)
; #pragma unroll
;                 for (int n = 0; n < 4; ++n) acc[m][n] = (f32x4){0.f, 0.f, 0.f, 0.f};
;             for (int kc = 0; kc < 4; ++kc) {
;                 const int c = j * 4 + kc;
;                 if (c + 1 < 16) BR_LOAD(c + 1, (c + 1) & 1);
;                 if (kc == 3) {
;                     const bf16_t* gp = Gt + (size_t)(rt * 128 + wm * 64 + fr) * ZC + j * 1024 + ct * 256 + wn * 64 + 4 * fq;
; #pragma unroll
;                     for (int m = 0; m < 4; ++m)
; #pragma unroll
;                         for (int n = 0; n < 4; ++n) gv[m][n] = *(const u32x2*)(gp + (size_t)m * 16 * ZC + n * 16);
;                 }
;                 LAS const unsigned char* st = lds + (c & 1) * STG;
; #pragma unroll
;                 for (int k = 0; k < 2; ++k) {
;                     __builtin_amdgcn_sched_barrier(0);
;                     bf16x8 af[4], bfr[4];
; #pragma unroll
;                     for (int m = 0; m < 4; ++m) af[m] = *(LAS const bf16x8*)(st + aoff + m * 2048 + k * 1024);
; #pragma unroll
;                     for (int n = 0; n < 4; ++n) bfr[n] = *(LAS const bf16x8*)(st + boff + n * 2048 + k * 1024);
; #pragma unroll
;     ...
; #pragma unroll
;             for (int m = 0; m < 4; ++m)
; #pragma unroll
;                 for (int n = 0; n < 4; ++n) { const u32x2 g = gv[m][n], sp = sum[m][n];
;                     const float s0_ = __builtin_bit_cast(float, sp.x << 16) + acc[m][n][0] * __builtin_bit_cast(float, g.x << 16), s1_ = __builtin_bit_cast(float, sp.x & 0xffff0000u) + acc[m][n][1] * __builtin_bit_cast(float, g.x & 0xffff0000u);
;                     const float s2_ = __builtin_bit_cast(float, sp.y << 16) + acc[m][n][2] * __builtin_bit_cast(float, g.y << 16), s3_ = __builtin_bit_cast(float, sp.y & 0xffff0000u) + acc[m][n][3] * __builtin_bit_cast(float, g.y & 0xffff0000u);
;                     sum[m][n] = (u32x2){cvtpk(s0_, s1_), cvtpk(s2_, s3_)}; }
	v_pk_fma_f32 v[210:211], v[38:39], v[206:207], v[210:211]
	v_pk_fma_f32 v[212:213], v[40:41], v[208:209], v[212:213]
	v_cvt_pk_bf16_f32 v84, v210, v211
	v_cvt_pk_bf16_f32 v85, v212, v213
	v_lshlrev_b32_e32 v206, 16, v118
	v_and_b32_e32 v207, 0xffff0000, v118
	v_lshlrev_b32_e32 v208, 16, v119
	v_and_b32_e32 v209, 0xffff0000, v119
	v_lshlrev_b32_e32 v210, 16, v86
	v_and_b32_e32 v211, 0xffff0000, v86
	v_lshlrev_b32_e32 v212, 16, v87
	v_and_b32_e32 v213, 0xffff0000, v87
	v_pk_fma_f32 v[210:211], v[42:43], v[206:207], v[210:211]
	v_pk_fma_f32 v[212:213], v[44:45], v[208:209], v[212:213]
	v_cvt_pk_bf16_f32 v86, v210, v211
	v_cvt_pk_bf16_f32 v87, v212, v213
	v_lshlrev_b32_e32 v206, 16, v120
	v_and_b32_e32 v207, 0xffff0000, v120
	v_lshlrev_b32_e32 v208, 16, v121
	v_and_b32_e32 v209, 0xffff0000, v121
	v_lshlrev_b32_e32 v210, 16, v88
	v_and_b32_e32 v211, 0xffff0000, v88
	v_lshlrev_b32_e32 v212, 16, v89
	v_and_b32_e32 v213, 0xffff0000, v89
	v_pk_fma_f32 v[210:211], v[46:47], v[206:207], v[210:211]
	v_pk_fma_f32 v[212:213], v[48:49], v[208:209], v[212:213]
	v_cvt_pk_bf16_f32 v88, v210, v211
	v_cvt_pk_bf16_f32 v89, v212, v213
	v_lshlrev_b32_e32 v206, 16, v122
	v_and_b32_e32 v207, 0xffff0000, v122
	v_lshlrev_b32_e32 v208, 16, v123
	v_and_b32_e32 v209, 0xffff0000, v123
	v_lshlrev_b32_e32 v210, 16, v90
	v_and_b32_e32 v211, 0xffff0000, v90
	v_lshlrev_b32_e32 v212, 16, v91
	v_and_b32_e32 v213, 0xffff0000, v91
	v_pk_fma_f32 v[210:211], v[50:51], v[206:207], v[210:211]
	v_pk_fma_f32 v[212:213], v[52:53], v[208:209], v[212:213]
	v_cvt_pk_bf16_f32 v90, v210, v211
	v_cvt_pk_bf16_f32 v91, v212, v213
	v_lshlrev_b32_e32 v206, 16, v124
	v_and_b32_e32 v207, 0xffff0000, v124
	v_lshlrev_b32_e32 v208, 16, v125
	v_and_b32_e32 v209, 0xffff0000, v125
	v_lshlrev_b32_e32 v210, 16, v92
	v_and_b32_e32 v211, 0xffff0000, v92
	v_lshlrev_b32_e32 v212, 16, v93
	v_and_b32_e32 v213, 0xffff0000, v93
	v_pk_fma_f32 v[210:211], v[54:55], v[206:207], v[210:211]
	v_pk_fma_f32 v[212:213], v[56:57], v[208:209], v[212:213]
	v_cvt_pk_bf16_f32 v92, v210, v211
	v_cvt_pk_bf16_f32 v93, v212, v213
	v_lshlrev_b32_e32 v206, 16, v126
	v_and_b32_e32 v207, 0xffff0000, v126
	v_lshlrev_b32_e32 v208, 16, v127
	v_and_b32_e32 v209, 0xffff0000, v127
	v_lshlrev_b32_e32 v210, 16, v94
	v_and_b32_e32 v211, 0xffff0000, v94
	v_lshlrev_b32_e32 v212, 16, v95
	v_and_b32_e32 v213, 0xffff0000, v95
	v_pk_fma_f32 v[210:211], v[58:59], v[206:207], v[210:211]
	v_pk_fma_f32 v[212:213], v[60:61], v[208:209], v[212:213]
	v_cvt_pk_bf16_f32 v94, v210, v211
	v_cvt_pk_bf16_f32 v95, v212, v213
	v_lshlrev_b32_e32 v206, 16, v128
	v_and_b32_e32 v207, 0xffff0000, v128
	v_lshlrev_b32_e32 v208, 16, v129
	v_and_b32_e32 v209, 0xffff0000, v129
	v_lshlrev_b32_e32 v210, 16, v96
	v_and_b32_e32 v211, 0xffff0000, v96
	v_lshlrev_b32_e32 v212, 16, v97
	v_and_b32_e32 v213, 0xffff0000, v97
	v_pk_fma_f32 v[210:211], v[62:63], v[206:207], v[210:211]
	v_pk_fma_f32 v[212:213], v[64:65], v[208:209], v[212:213]
	v_cvt_pk_bf16_f32 v96, v210, v211
	v_cvt_pk_bf16_f32 v97, v212, v213
	s_add_u32 s66, s64, 0x700
	s_addc_u32 s67, s65, 0
	s_add_u32 s70, s68, 0x180100
	s_addc_u32 s71, s69, 0
	s_add_u32 s72, s70, 0x10000
	s_addc_u32 s73, s71, 0
	s_add_i32 m0, s78, 0x18000
	s_nop 0
	global_load_lds_dwordx4 v197, s[66:67]
	s_add_i32 m0, s78, 0x1a000
	s_nop 0
	global_load_lds_dwordx4 v198, s[66:67]
	s_add_i32 m0, s78, 0x1c000
	s_nop 0
	global_load_lds_dwordx4 v199, s[70:71]
	s_add_i32 m0, s78, 0x1e000
	s_nop 0
	global_load_lds_dwordx4 v200, s[70:71]
	s_add_i32 m0, s78, 0x20800
	s_nop 0
	global_load_lds_dwordx4 v199, s[72:73]
	s_add_i32 m0, s78, 0x22800
	s_nop 0
	global_load_lds_dwordx4 v200, s[72:73]
	ds_read_b128 v[130:133], v214 offset:0
	ds_read_b128 v[134:137], v214 offset:2048
	ds_read_b128 v[138:141], v214 offset:4096
	ds_read_b128 v[142:145], v214 offset:6144
	ds_read_b128 v[162:165], v217 offset:0
	ds_read_b128 v[166:169], v217 offset:2048
	ds_read_b128 v[170:173], v217 offset:4096
	ds_read_b128 v[174:177], v217 offset:6144
	ds_read_b128 v[146:149], v214 offset:1024
	ds_read_b128 v[150:153], v214 offset:3072
	ds_read_b128 v[154:157], v214 offset:5120
	ds_read_b128 v[158:161], v214 offset:7168
	ds_read_b128 v[178:181], v217 offset:1024
	ds_read_b128 v[182:185], v217 offset:3072
	ds_read_b128 v[186:189], v217 offset:5120
	ds_read_b128 v[190:193], v217 offset:7168
	s_waitcnt lgkmcnt(8)
	v_mfma_f32_16x16x32_bf16 v[2:5], v[162:165], v[130:133], 0
	v_mfma_f32_16x16x32_bf16 v[6:9], v[166:169], v[130:133], 0
	v_mfma_f32_16x16x32_bf16 v[10:13], v[170:173], v[130:133], 0
	v_mfma_f32_16x16x32_bf16 v[14:17], v[174:177], v[130:133], 0
	v_mfma_f32_16x16x32_bf16 v[18:21], v[162:165], v[134:137], 0
	v_mfma_f32_16x16x32_bf16 v[22:25], v[166:169], v[134:137], 0
	v_mfma_f32_16x16x32_bf16 v[26:29], v[170:173], v[134:137], 0
	v_mfma_f32_16x16x32_bf16 v[30:33], v[174:177], v[134:137], 0
	v_mfma_f32_16x16x32_bf16 v[34:37], v[162:165], v[138:141], 0
	v_mfma_f32_16x16x32_bf16 v[38:41], v[166:169], v[138:141], 0
	v_mfma_f32_16x16x32_bf16 v[42:45], v[170:173], v[138:141], 0
	v_mfma_f32_16x16x32_bf16 v[46:49], v[174:177], v[138:141], 0
	v_mfma_f32_16x16x32_bf16 v[50:53], v[162:165], v[142:145], 0
	v_mfma_f32_16x16x32_bf16 v[54:57], v[166:169], v[142:145], 0
	v_mfma_f32_16x16x32_bf16 v[58:61], v[170:173], v[142:145], 0
	v_mfma_f32_16x16x32_bf16 v[62:65], v[174:177], v[142:145], 0
	s_waitcnt lgkmcnt(0)
	v_mfma_f32_16x16x32_bf16 v[2:5], v[178:181], v[146:149], v[2:5]
	v_mfma_f32_16x16x32_bf16 v[6:9], v[182:185], v[146:149], v[6:9]
	v_mfma_f32_16x16x32_bf16 v[10:13], v[186:189], v[146:149], v[10:13]
	v_mfma_f32_16x16x32_bf16 v[14:17], v[190:193], v[146:149], v[14:17]
	v_mfma_f32_16x16x32_bf16 v[18:21], v[178:181], v[150:153], v[18:21]
	v_mfma_f32_16x16x32_bf16 v[22:25], v[182:185], v[150:153], v[22:25]
	v_mfma_f32_16x16x32_bf16 v[26:29], v[186:189], v[150:153], v[26:29]
	v_mfma_f32_16x16x32_bf16 v[30:33], v[190:193], v[150:153], v[30:33]
	v_mfma_f32_16x16x32_bf16 v[34:37], v[178:181], v[154:157], v[34:37]
	v_mfma_f32_16x16x32_bf16 v[38:41], v[182:185], v[154:157], v[38:41]
	v_mfma_f32_16x16x32_bf16 v[42:45], v[186:189], v[154:157], v[42:45]
	v_mfma_f32_16x16x32_bf16 v[46:49], v[190:193], v[154:157], v[46:49]
	v_mfma_f32_16x16x32_bf16 v[50:53], v[178:181], v[158:161], v[50:53]
	v_mfma_f32_16x16x32_bf16 v[54:57], v[182:185], v[158:161], v[54:57]
	v_mfma_f32_16x16x32_bf16 v[58:61], v[186:189], v[158:161], v[58:61]
	v_mfma_f32_16x16x32_bf16 v[62:65], v[190:193], v[158:161], v[62:65]
	s_waitcnt vmcnt(6)
	s_barrier
; #define LAS __attribute__((address_space(3)))
; __device__ __forceinline__ void branch_phase(LAS unsigned char* lds, const bf16_t* __restrict__ O, const bf16_t* __restrict__ Wb, const bf16_t* __restrict__ Gt, bf16_t* __restrict__ MG, int tg, int wv) {
;     ...
;         BR_LOAD(0, 0);
;         asm volatile("s_waitcnt vmcnt(0)" ::: "memory"); __syncthreads();
;         for (int j = 0; j < 4; ++j) {
;             u32x2 gv[4][4];
;             f32x4 acc[4][4];
; #pragma unroll
;             for (int m = 0; m < 4; ++m)
; #pragma unroll
;                 for (int n = 0; n < 4; ++n) acc[m][n] = (f32x4){0.f, 0.f, 0.f, 0.f};
;             for (int kc = 0; kc < 4; ++kc) {
;                 const int c = j * 4 + kc;
;                 if (c + 1 < 16) BR_LOAD(c + 1, (c + 1) & 1);
;                 if (kc == 3) {
;                     const bf16_t* gp = Gt + (size_t)(rt * 128 + wm * 64 + fr) * ZC + j * 1024 + ct * 256 + wn * 64 + 4 * fq;
; #pragma unroll
;                     for (int m = 0; m < 4; ++m)
; #pragma unroll
;                         for (int n = 0; n < 4; ++n) gv[m][n] = *(const u32x2*)(gp + (size_t)m * 16 * ZC + n * 16);
;                 }
;                 LAS const unsigned char* st = lds + (c & 1) * STG;
; #pragma unroll
;                 for (int k = 0; k < 2; ++k) {
;                     __builtin_amdgcn_sched_barrier(0);
;                     bf16x8 af[4], bfr[4];
; #pragma unroll
;                     for (int m = 0; m < 4; ++m) af[m] = *(LAS const bf16x8*)(st + aoff + m * 2048 + k * 1024);
; #pragma unroll
;                     for (int n = 0; n < 4; ++n) bfr[n] = *(LAS const bf16x8*)(st + boff + n * 2048 + k * 1024);
; #pragma unroll
;                     for (int m = 0; m < 4; ++m)
; #pragma unroll
;                         for (int n = 0; n < 4; ++n) acc[m][n] = __builtin_amdgcn_mfma_f32_16x16x32_bf16(bfr[n], af[m], acc[m][n], 0, 0, 0);
;                 }
;                 asm volatile("s_waitcnt vmcnt(0)" ::: "memory"); __syncthreads();
	s_add_u32 s66, s64, 0x780
	s_addc_u32 s67, s65, 0
	s_add_u32 s70, s68, 0x180180
	s_addc_u32 s71, s69, 0
	s_add_u32 s72, s70, 0x10000
	s_addc_u32 s73, s71, 0
	s_add_i32 m0, s78, 0x0
	s_nop 0
	global_load_lds_dwordx4 v197, s[66:67]
	s_add_i32 m0, s78, 0x2000
	s_nop 0
	global_load_lds_dwordx4 v198, s[66:67]
	s_add_i32 m0, s78, 0x4000
	s_nop 0
	global_load_lds_dwordx4 v199, s[70:71]
	s_add_i32 m0, s78, 0x6000
	s_nop 0
	global_load_lds_dwordx4 v200, s[70:71]
	s_add_i32 m0, s78, 0x8000
	s_nop 0
	global_load_lds_dwordx4 v199, s[72:73]
	s_add_i32 m0, s78, 0xa000
	s_nop 0
	global_load_lds_dwordx4 v200, s[72:73]
	s_add_u32 s80, s74, 0x1800
	s_addc_u32 s81, s75, 0
	global_load_dwordx2 v[98:99], v204, s[80:81] offset:0
	global_load_dwordx2 v[100:101], v204, s[80:81] offset:32
	global_load_dwordx2 v[102:103], v204, s[80:81] offset:64
	global_load_dwordx2 v[104:105], v204, s[80:81] offset:96
	s_add_u32 s80, s80, 0x20000
	s_addc_u32 s81, s81, 0
	global_load_dwordx2 v[106:107], v204, s[80:81] offset:0
	global_load_dwordx2 v[108:109], v204, s[80:81] offset:32
	global_load_dwordx2 v[110:111], v204, s[80:81] offset:64
	global_load_dwordx2 v[112:113], v204, s[80:81] offset:96
	s_add_u32 s80, s80, 0x20000
	s_addc_u32 s81, s81, 0
	global_load_dwordx2 v[114:115], v204, s[80:81] offset:0
	global_load_dwordx2 v[116:117], v204, s[80:81] offset:32
	global_load_dwordx2 v[118:119], v204, s[80:81] offset:64
	global_load_dwordx2 v[120:121], v204, s[80:81] offset:96
	s_add_u32 s80, s80, 0x20000
	s_addc_u32 s81, s81, 0
	global_load_dwordx2 v[122:123], v204, s[80:81] offset:0
	global_load_dwordx2 v[124:125], v204, s[80:81] offset:32
	global_load_dwordx2 v[126:127], v204, s[80:81] offset:64
	global_load_dwordx2 v[128:129], v204, s[80:81] offset:96
	ds_read_b128 v[130:133], v215 offset:0
	ds_read_b128 v[134:137], v215 offset:2048
	ds_read_b128 v[138:141], v215 offset:4096
	ds_read_b128 v[142:145], v215 offset:6144
	ds_read_b128 v[162:165], v218 offset:0
	ds_read_b128 v[166:169], v218 offset:2048
	ds_read_b128 v[170:173], v218 offset:4096
	ds_read_b128 v[174:177], v218 offset:6144
	ds_read_b128 v[146:149], v215 offset:1024
	ds_read_b128 v[150:153], v215 offset:3072
	ds_read_b128 v[154:157], v215 offset:5120
	ds_read_b128 v[158:161], v215 offset:7168
	ds_read_b128 v[178:181], v218 offset:1024
	ds_read_b128 v[182:185], v218 offset:3072
	ds_read_b128 v[186:189], v218 offset:5120
	ds_read_b128 v[190:193], v218 offset:7168
	s_waitcnt lgkmcnt(8)
	v_mfma_f32_16x16x32_bf16 v[2:5], v[162:165], v[130:133], v[2:5]
	v_mfma_f32_16x16x32_bf16 v[6:9], v[166:169], v[130:133], v[6:9]
	v_mfma_f32_16x16x32_bf16 v[10:13], v[170:173], v[130:133], v[10:13]
	v_mfma_f32_16x16x32_bf16 v[14:17], v[174:177], v[130:133], v[14:17]
	v_mfma_f32_16x16x32_bf16 v[18:21], v[162:165], v[134:137], v[18:21]
	v_mfma_f32_16x16x32_bf16 v[22:25], v[166:169], v[134:137], v[22:25]
	v_mfma_f32_16x16x32_bf16 v[26:29], v[170:173], v[134:137], v[26:29]
	v_mfma_f32_16x16x32_bf16 v[30:33], v[174:177], v[134:137], v[30:33]
	v_mfma_f32_16x16x32_bf16 v[34:37], v[162:165], v[138:141], v[34:37]
	v_mfma_f32_16x16x32_bf16 v[38:41], v[166:169], v[138:141], v[38:41]
	v_mfma_f32_16x16x32_bf16 v[42:45], v[170:173], v[138:141], v[42:45]
	v_mfma_f32_16x16x32_bf16 v[46:49], v[174:177], v[138:141], v[46:49]
	v_mfma_f32_16x16x32_bf16 v[50:53], v[162:165], v[142:145], v[50:53]
	v_mfma_f32_16x16x32_bf16 v[54:57], v[166:169], v[142:145], v[54:57]
	v_mfma_f32_16x16x32_bf16 v[58:61], v[170:173], v[142:145], v[58:61]
	v_mfma_f32_16x16x32_bf16 v[62:65], v[174:177], v[142:145], v[62:65]
	s_waitcnt lgkmcnt(0)
	v_mfma_f32_16x16x32_bf16 v[2:5], v[178:181], v[146:149], v[2:5]
	v_mfma_f32_16x16x32_bf16 v[6:9], v[182:185], v[146:149], v[6:9]
	v_mfma_f32_16x16x32_bf16 v[10:13], v[186:189], v[146:149], v[10:13]
	v_mfma_f32_16x16x32_bf16 v[14:17], v[190:193], v[146:149], v[14:17]
	v_mfma_f32_16x16x32_bf16 v[18:21], v[178:181], v[150:153], v[18:21]
	v_mfma_f32_16x16x32_bf16 v[22:25], v[182:185], v[150:153], v[22:25]
	v_mfma_f32_16x16x32_bf16 v[26:29], v[186:189], v[150:153], v[26:29]
	v_mfma_f32_16x16x32_bf16 v[30:33], v[190:193], v[150:153], v[30:33]
	v_mfma_f32_16x16x32_bf16 v[34:37], v[178:181], v[154:157], v[34:37]
	v_mfma_f32_16x16x32_bf16 v[38:41], v[182:185], v[154:157], v[38:41]
	v_mfma_f32_16x16x32_bf16 v[42:45], v[186:189], v[154:157], v[42:45]
	v_mfma_f32_16x16x32_bf16 v[46:49], v[190:193], v[154:157], v[46:49]
	v_mfma_f32_16x16x32_bf16 v[50:53], v[178:181], v[158:161], v[50:53]
	v_mfma_f32_16x16x32_bf16 v[54:57], v[182:185], v[158:161], v[54:57]
	v_mfma_f32_16x16x32_bf16 v[58:61], v[186:189], v[158:161], v[58:61]
	v_mfma_f32_16x16x32_bf16 v[62:65], v[190:193], v[158:161], v[62:65]
	s_waitcnt vmcnt(22)
	s_barrier
; #define LAS __attribute__((address_space(3)))
; __device__ __forceinline__ void branch_phase(LAS unsigned char* lds, const bf16_t* __restrict__ O, const bf16_t* __restrict__ Wb, const bf16_t* __restrict__ Gt, bf16_t* __restrict__ MG, int tg, int wv) {
;     ...
;                 LAS const unsigned char* st = lds + (c & 1) * STG;
; #pragma unroll
;                 for (int k = 0; k < 2; ++k) {
;                     __builtin_amdgcn_sched_barrier(0);
;                     bf16x8 af[4], bfr[4];
; #pragma unroll
;                     for (int m = 0; m < 4; ++m) af[m] = *(LAS const bf16x8*)(st + aoff + m * 2048 + k * 1024);
; #pragma unroll
;                     for (int n = 0; n < 4; ++n) bfr[n] = *(LAS const bf16x8*)(st + boff + n * 2048 + k * 1024);
; #pragma unroll
;                     for (int m = 0; m < 4; ++m)
; #pragma unroll
;                         for (int n = 0; n < 4; ++n) acc[m][n] = __builtin_amdgcn_mfma_f32_16x16x32_bf16(bfr[n], af[m], acc[m][n], 0, 0, 0);
;                 }
;                 asm volatile("s_waitcnt vmcnt(0)" ::: "memory"); __syncthreads();
	ds_read_b128 v[130:133], v216 offset:0
	ds_read_b128 v[134:137], v216 offset:2048
	ds_read_b128 v[138:141], v216 offset:4096
	ds_read_b128 v[142:145], v216 offset:6144
	ds_read_b128 v[162:165], v219 offset:0
	ds_read_b128 v[166:169], v219 offset:2048
	ds_read_b128 v[170:173], v219 offset:4096
	ds_read_b128 v[174:177], v219 offset:6144
	ds_read_b128 v[146:149], v216 offset:1024
	ds_read_b128 v[150:153], v216 offset:3072
	ds_read_b128 v[154:157], v216 offset:5120
	ds_read_b128 v[158:161], v216 offset:7168
	ds_read_b128 v[178:181], v219 offset:1024
	ds_read_b128 v[182:185], v219 offset:3072
	ds_read_b128 v[186:189], v219 offset:5120
	ds_read_b128 v[190:193], v219 offset:7168
	s_waitcnt lgkmcnt(8)
	v_mfma_f32_16x16x32_bf16 v[2:5], v[162:165], v[130:133], v[2:5]
	v_mfma_f32_16x16x32_bf16 v[6:9], v[166:169], v[130:133], v[6:9]
	v_mfma_f32_16x16x32_bf16 v[10:13], v[170:173], v[130:133], v[10:13]
	v_mfma_f32_16x16x32_bf16 v[14:17], v[174:177], v[130:133], v[14:17]
	v_mfma_f32_16x16x32_bf16 v[18:21], v[162:165], v[134:137], v[18:21]
	v_mfma_f32_16x16x32_bf16 v[22:25], v[166:169], v[134:137], v[22:25]
	v_mfma_f32_16x16x32_bf16 v[26:29], v[170:173], v[134:137], v[26:29]
	v_mfma_f32_16x16x32_bf16 v[30:33], v[174:177], v[134:137], v[30:33]
	v_mfma_f32_16x16x32_bf16 v[34:37], v[162:165], v[138:141], v[34:37]
	v_mfma_f32_16x16x32_bf16 v[38:41], v[166:169], v[138:141], v[38:41]
	v_mfma_f32_16x16x32_bf16 v[42:45], v[170:173], v[138:141], v[42:45]
	v_mfma_f32_16x16x32_bf16 v[46:49], v[174:177], v[138:141], v[46:49]
	v_mfma_f32_16x16x32_bf16 v[50:53], v[162:165], v[142:145], v[50:53]
	v_mfma_f32_16x16x32_bf16 v[54:57], v[166:169], v[142:145], v[54:57]
	v_mfma_f32_16x16x32_bf16 v[58:61], v[170:173], v[142:145], v[58:61]
	v_mfma_f32_16x16x32_bf16 v[62:65], v[174:177], v[142:145], v[62:65]
	s_waitcnt lgkmcnt(0)
	v_mfma_f32_16x16x32_bf16 v[2:5], v[178:181], v[146:149], v[2:5]
	v_mfma_f32_16x16x32_bf16 v[6:9], v[182:185], v[146:149], v[6:9]
	v_mfma_f32_16x16x32_bf16 v[10:13], v[186:189], v[146:149], v[10:13]
	v_mfma_f32_16x16x32_bf16 v[14:17], v[190:193], v[146:149], v[14:17]
	v_mfma_f32_16x16x32_bf16 v[18:21], v[178:181], v[150:153], v[18:21]
	v_mfma_f32_16x16x32_bf16 v[22:25], v[182:185], v[150:153], v[22:25]
	v_mfma_f32_16x16x32_bf16 v[26:29], v[186:189], v[150:153], v[26:29]
	v_mfma_f32_16x16x32_bf16 v[30:33], v[190:193], v[150:153], v[30:33]
	v_mfma_f32_16x16x32_bf16 v[34:37], v[178:181], v[154:157], v[34:37]
	v_mfma_f32_16x16x32_bf16 v[38:41], v[182:185], v[154:157], v[38:41]
	v_mfma_f32_16x16x32_bf16 v[42:45], v[186:189], v[154:157], v[42:45]
	v_mfma_f32_16x16x32_bf16 v[46:49], v[190:193], v[154:157], v[46:49]
	v_mfma_f32_16x16x32_bf16 v[50:53], v[178:181], v[158:161], v[50:53]
	v_mfma_f32_16x16x32_bf16 v[54:57], v[182:185], v[158:161], v[54:57]
	v_mfma_f32_16x16x32_bf16 v[58:61], v[186:189], v[158:161], v[58:61]
	v_mfma_f32_16x16x32_bf16 v[62:65], v[190:193], v[158:161], v[62:65]
	s_waitcnt vmcnt(16)
	s_barrier
	ds_read_b128 v[130:133], v214 offset:0
	ds_read_b128 v[134:137], v214 offset:2048
	ds_read_b128 v[138:141], v214 offset:4096
	ds_read_b128 v[142:145], v214 offset:6144
	ds_read_b128 v[162:165], v217 offset:0
	ds_read_b128 v[166:169], v217 offset:2048
	ds_read_b128 v[170:173], v217 offset:4096
	ds_read_b128 v[174:177], v217 offset:6144
	ds_read_b128 v[146:149], v214 offset:1024
	ds_read_b128 v[150:153], v214 offset:3072
	ds_read_b128 v[154:157], v214 offset:5120
	ds_read_b128 v[158:161], v214 offset:7168
	ds_read_b128 v[178:181], v217 offset:1024
	ds_read_b128 v[182:185], v217 offset:3072
	ds_read_b128 v[186:189], v217 offset:5120
	ds_read_b128 v[190:193], v217 offset:7168
	s_waitcnt lgkmcnt(8)
	v_mfma_f32_16x16x32_bf16 v[2:5], v[162:165], v[130:133], v[2:5]
	v_mfma_f32_16x16x32_bf16 v[6:9], v[166:169], v[130:133], v[6:9]
	v_mfma_f32_16x16x32_bf16 v[10:13], v[170:173], v[130:133], v[10:13]
	v_mfma_f32_16x16x32_bf16 v[14:17], v[174:177], v[130:133], v[14:17]
	v_mfma_f32_16x16x32_bf16 v[18:21], v[162:165], v[134:137], v[18:21]
	v_mfma_f32_16x16x32_bf16 v[22:25], v[166:169], v[134:137], v[22:25]
	v_mfma_f32_16x16x32_bf16 v[26:29], v[170:173], v[134:137], v[26:29]
	v_mfma_f32_16x16x32_bf16 v[30:33], v[174:177], v[134:137], v[30:33]
	v_mfma_f32_16x16x32_bf16 v[34:37], v[162:165], v[138:141], v[34:37]
	v_mfma_f32_16x16x32_bf16 v[38:41], v[166:169], v[138:141], v[38:41]
	v_mfma_f32_16x16x32_bf16 v[42:45], v[170:173], v[138:141], v[42:45]
	v_mfma_f32_16x16x32_bf16 v[46:49], v[174:177], v[138:141], v[46:49]
	v_mfma_f32_16x16x32_bf16 v[50:53], v[162:165], v[142:145], v[50:53]
	v_mfma_f32_16x16x32_bf16 v[54:57], v[166:169], v[142:145], v[54:57]
	v_mfma_f32_16x16x32_bf16 v[58:61], v[170:173], v[142:145], v[58:61]
	v_mfma_f32_16x16x32_bf16 v[62:65], v[174:177], v[142:145], v[62:65]
	s_waitcnt lgkmcnt(0)
	v_mfma_f32_16x16x32_bf16 v[2:5], v[178:181], v[146:149], v[2:5]
	v_mfma_f32_16x16x32_bf16 v[6:9], v[182:185], v[146:149], v[6:9]
	v_mfma_f32_16x16x32_bf16 v[10:13], v[186:189], v[146:149], v[10:13]
	v_mfma_f32_16x16x32_bf16 v[14:17], v[190:193], v[146:149], v[14:17]
	v_mfma_f32_16x16x32_bf16 v[18:21], v[178:181], v[150:153], v[18:21]
	v_mfma_f32_16x16x32_bf16 v[22:25], v[182:185], v[150:153], v[22:25]
	v_mfma_f32_16x16x32_bf16 v[26:29], v[186:189], v[150:153], v[26:29]
	v_mfma_f32_16x16x32_bf16 v[30:33], v[190:193], v[150:153], v[30:33]
	v_mfma_f32_16x16x32_bf16 v[34:37], v[178:181], v[154:157], v[34:37]
	v_mfma_f32_16x16x32_bf16 v[38:41], v[182:185], v[154:157], v[38:41]
	v_mfma_f32_16x16x32_bf16 v[42:45], v[186:189], v[154:157], v[42:45]
	v_mfma_f32_16x16x32_bf16 v[46:49], v[190:193], v[154:157], v[46:49]
	v_mfma_f32_16x16x32_bf16 v[50:53], v[178:181], v[158:161], v[50:53]
	v_mfma_f32_16x16x32_bf16 v[54:57], v[182:185], v[158:161], v[54:57]
	v_mfma_f32_16x16x32_bf16 v[58:61], v[186:189], v[158:161], v[58:61]
	v_mfma_f32_16x16x32_bf16 v[62:65], v[190:193], v[158:161], v[62:65]
	s_waitcnt vmcnt(0)
; __device__ __forceinline__ unsigned cvtpk(float lo, float hi) { f32x2 v = {lo, hi}; bf16x2_t b = __builtin_convertvector(v, bf16x2_t); return __builtin_bit_cast(unsigned, b); }
; __device__ __forceinline__ void branch_phase(LAS unsigned char* lds, const bf16_t* __restrict__ O, const bf16_t* __restrict__ Wb, const bf16_t* __restrict__ Gt, bf16_t* __restrict__ MG, int tg, int wv) {
;     ...
; #pragma unroll
;             for (int m = 0; m < 4; ++m)
; #pragma unroll
;                 for (int n = 0; n < 4; ++n) { const u32x2 g = gv[m][n], sp = sum[m][n];
;                     const float s0_ = __builtin_bit_cast(float, sp.x << 16) + acc[m][n][0] * __builtin_bit_cast(float, g.x << 16), s1_ = __builtin_bit_cast(float, sp.x & 0xffff0000u) + acc[m][n][1] * __builtin_bit_cast(float, g.x & 0xffff0000u);
;                     const float s2_ = __builtin_bit_cast(float, sp.y << 16) + acc[m][n][2] * __builtin_bit_cast(float, g.y << 16), s3_ = __builtin_bit_cast(float, sp.y & 0xffff0000u) + acc[m][n][3] * __builtin_bit_cast(float, g.y & 0xffff0000u);
;                     sum[m][n] = (u32x2){cvtpk(s0_, s1_), cvtpk(s2_, s3_)}; }
	s_nop 7
	v_lshlrev_b32_e32 v206, 16, v98
	v_and_b32_e32 v207, 0xffff0000, v98
	v_lshlrev_b32_e32 v208, 16, v99
	v_and_b32_e32 v209, 0xffff0000, v99
	v_lshlrev_b32_e32 v210, 16, v66
	v_and_b32_e32 v211, 0xffff0000, v66
	v_lshlrev_b32_e32 v212, 16, v67
	v_and_b32_e32 v213, 0xffff0000, v67
	v_pk_fma_f32 v[210:211], v[2:3], v[206:207], v[210:211]
	v_pk_fma_f32 v[212:213], v[4:5], v[208:209], v[212:213]
	v_cvt_pk_bf16_f32 v66, v210, v211
	v_cvt_pk_bf16_f32 v67, v212, v213
	v_lshlrev_b32_e32 v206, 16, v100
	v_and_b32_e32 v207, 0xffff0000, v100
	v_lshlrev_b32_e32 v208, 16, v101
	v_and_b32_e32 v209, 0xffff0000, v101
	v_lshlrev_b32_e32 v210, 16, v68
	v_and_b32_e32 v211, 0xffff0000, v68
	v_lshlrev_b32_e32 v212, 16, v69
	v_and_b32_e32 v213, 0xffff0000, v69
	v_pk_fma_f32 v[210:211], v[6:7], v[206:207], v[210:211]
	v_pk_fma_f32 v[212:213], v[8:9], v[208:209], v[212:213]
	v_cvt_pk_bf16_f32 v68, v210, v211
	v_cvt_pk_bf16_f32 v69, v212, v213
	v_lshlrev_b32_e32 v206, 16, v102
	v_and_b32_e32 v207, 0xffff0000, v102
	v_lshlrev_b32_e32 v208, 16, v103
	v_and_b32_e32 v209, 0xffff0000, v103
	v_lshlrev_b32_e32 v210, 16, v70
	v_and_b32_e32 v211, 0xffff0000, v70
	v_lshlrev_b32_e32 v212, 16, v71
	v_and_b32_e32 v213, 0xffff0000, v71
	v_pk_fma_f32 v[210:211], v[10:11], v[206:207], v[210:211]
	v_pk_fma_f32 v[212:213], v[12:13], v[208:209], v[212:213]
	v_cvt_pk_bf16_f32 v70, v210, v211
	v_cvt_pk_bf16_f32 v71, v212, v213
	v_lshlrev_b32_e32 v206, 16, v104
	v_and_b32_e32 v207, 0xffff0000, v104
	v_lshlrev_b32_e32 v208, 16, v105
	v_and_b32_e32 v209, 0xffff0000, v105
	v_lshlrev_b32_e32 v210, 16, v72
	v_and_b32_e32 v211, 0xffff0000, v72
	v_lshlrev_b32_e32 v212, 16, v73
	v_and_b32_e32 v213, 0xffff0000, v73
	v_pk_fma_f32 v[210:211], v[14:15], v[206:207], v[210:211]
	v_pk_fma_f32 v[212:213], v[16:17], v[208:209], v[212:213]
	v_cvt_pk_bf16_f32 v72, v210, v211
	v_cvt_pk_bf16_f32 v73, v212, v213
	v_lshlrev_b32_e32 v206, 16, v106
	v_and_b32_e32 v207, 0xffff0000, v106
	v_lshlrev_b32_e32 v208, 16, v107
	v_and_b32_e32 v209, 0xffff0000, v107
	v_lshlrev_b32_e32 v210, 16, v74
	v_and_b32_e32 v211, 0xffff0000, v74
	v_lshlrev_b32_e32 v212, 16, v75
	v_and_b32_e32 v213, 0xffff0000, v75
	v_pk_fma_f32 v[210:211], v[18:19], v[206:207], v[210:211]
	v_pk_fma_f32 v[212:213], v[20:21], v[208:209], v[212:213]
	v_cvt_pk_bf16_f32 v74, v210, v211
	v_cvt_pk_bf16_f32 v75, v212, v213
	v_lshlrev_b32_e32 v206, 16, v108
	v_and_b32_e32 v207, 0xffff0000, v108
	v_lshlrev_b32_e32 v208, 16, v109
	v_and_b32_e32 v209, 0xffff0000, v109
	v_lshlrev_b32_e32 v210, 16, v76
	v_and_b32_e32 v211, 0xffff0000, v76
	v_lshlrev_b32_e32 v212, 16, v77
	v_and_b32_e32 v213, 0xffff0000, v77
	v_pk_fma_f32 v[210:211], v[22:23], v[206:207], v[210:211]
	v_pk_fma_f32 v[212:213], v[24:25], v[208:209], v[212:213]
	v_cvt_pk_bf16_f32 v76, v210, v211
	v_cvt_pk_bf16_f32 v77, v212, v213
	v_lshlrev_b32_e32 v206, 16, v110
	v_and_b32_e32 v207, 0xffff0000, v110
	v_lshlrev_b32_e32 v208, 16, v111
	v_and_b32_e32 v209, 0xffff0000, v111
	v_lshlrev_b32_e32 v210, 16, v78
	v_and_b32_e32 v211, 0xffff0000, v78
	v_lshlrev_b32_e32 v212, 16, v79
	v_and_b32_e32 v213, 0xffff0000, v79
	v_pk_fma_f32 v[210:211], v[26:27], v[206:207], v[210:211]
	v_pk_fma_f32 v[212:213], v[28:29], v[208:209], v[212:213]
	v_cvt_pk_bf16_f32 v78, v210, v211
	v_cvt_pk_bf16_f32 v79, v212, v213
	v_lshlrev_b32_e32 v206, 16, v112
	v_and_b32_e32 v207, 0xffff0000, v112
	v_lshlrev_b32_e32 v208, 16, v113
	v_and_b32_e32 v209, 0xffff0000, v113
	v_lshlrev_b32_e32 v210, 16, v80
	v_and_b32_e32 v211, 0xffff0000, v80
	v_lshlrev_b32_e32 v212, 16, v81
	v_and_b32_e32 v213, 0xffff0000, v81
	v_pk_fma_f32 v[210:211], v[30:31], v[206:207], v[210:211]
	v_pk_fma_f32 v[212:213], v[32:33], v[208:209], v[212:213]
	v_cvt_pk_bf16_f32 v80, v210, v211
	v_cvt_pk_bf16_f32 v81, v212, v213
	v_lshlrev_b32_e32 v206, 16, v114
	v_and_b32_e32 v207, 0xffff0000, v114
	v_lshlrev_b32_e32 v208, 16, v115
	v_and_b32_e32 v209, 0xffff0000, v115
	v_lshlrev_b32_e32 v210, 16, v82
	v_and_b32_e32 v211, 0xffff0000, v82
	v_lshlrev_b32_e32 v212, 16, v83
	v_and_b32_e32 v213, 0xffff0000, v83
	v_pk_fma_f32 v[210:211], v[34:35], v[206:207], v[210:211]
	v_pk_fma_f32 v[212:213], v[36:37], v[208:209], v[212:213]
	v_cvt_pk_bf16_f32 v82, v210, v211
	v_cvt_pk_bf16_f32 v83, v212, v213
	v_lshlrev_b32_e32 v206, 16, v116
	v_and_b32_e32 v207, 0xffff0000, v116
	v_lshlrev_b32_e32 v208, 16, v117
	v_and_b32_e32 v209, 0xffff0000, v117
	v_lshlrev_b32_e32 v210, 16, v84
	v_and_b32_e32 v211, 0xffff0000, v84
	v_lshlrev_b32_e32 v212, 16, v85
	v_and_b32_e32 v213, 0xffff0000, v85
	v_pk_fma_f32 v[210:211], v[38:39], v[206:207], v[210:211]
	v_pk_fma_f32 v[212:213], v[40:41], v[208:209], v[212:213]
	v_cvt_pk_bf16_f32 v84, v210, v211
	v_cvt_pk_bf16_f32 v85, v212, v213
	v_lshlrev_b32_e32 v206, 16, v118
	v_and_b32_e32 v207, 0xffff0000, v118
	v_lshlrev_b32_e32 v208, 16, v119
	v_and_b32_e32 v209, 0xffff0000, v119
	v_lshlrev_b32_e32 v210, 16, v86
	v_and_b32_e32 v211, 0xffff0000, v86
	v_lshlrev_b32_e32 v212, 16, v87
	v_and_b32_e32 v213, 0xffff0000, v87
; __device__ __forceinline__ unsigned cvtpk(float lo, float hi) { f32x2 v = {lo, hi}; bf16x2_t b = __builtin_convertvector(v, bf16x2_t); return __builtin_bit_cast(unsigned, b); }
; __device__ __forceinline__ void branch_phase(LAS unsigned char* lds, const bf16_t* __restrict__ O, const bf16_t* __restrict__ Wb, const bf16_t* __restrict__ Gt, bf16_t* __restrict__ MG, int tg, int wv) {
;     ...
; #pragma unroll
;             for (int m = 0; m < 4; ++m)
; #pragma unroll
;                 for (int n = 0; n < 4; ++n) { const u32x2 g = gv[m][n], sp = sum[m][n];
;                     const float s0_ = __builtin_bit_cast(float, sp.x << 16) + acc[m][n][0] * __builtin_bit_cast(float, g.x << 16), s1_ = __builtin_bit_cast(float, sp.x & 0xffff0000u) + acc[m][n][1] * __builtin_bit_cast(float, g.x & 0xffff0000u);
;                     const float s2_ = __builtin_bit_cast(float, sp.y << 16) + acc[m][n][2] * __builtin_bit_cast(float, g.y << 16), s3_ = __builtin_bit_cast(float, sp.y & 0xffff0000u) + acc[m][n][3] * __builtin_bit_cast(float, g.y & 0xffff0000u);
;                     sum[m][n] = (u32x2){cvtpk(s0_, s1_), cvtpk(s2_, s3_)}; }
;         }
;     ...
; #pragma unroll
;         for (int m = 0; m < 4; ++m)
; #pragma unroll
;             for (int np = 0; np < 2; ++np) { u32x2 a = sum[m][2 * np], b = sum[m][2 * np + 1];
;                 asm volatile("s_nop 1\n\tv_permlane16_swap_b32 %0, %1\n\ts_nop 1" : "+v"(a.x), "+v"(b.x));
;                 asm volatile("s_nop 1\n\tv_permlane16_swap_b32 %0, %1\n\ts_nop 1" : "+v"(a.y), "+v"(b.y));
;                 *(u32x4*)(MG + (size_t)(rt * 128 + wm * 64 + m * 16 + fr) * 1024 + ct * 256 + wn * 64 + np * 32 + (fq & 1) * 16 + (fq >> 1) * 8) = (u32x4){a.x, a.y, b.x, b.y}; }
	v_pk_fma_f32 v[210:211], v[42:43], v[206:207], v[210:211]
	v_pk_fma_f32 v[212:213], v[44:45], v[208:209], v[212:213]
	v_cvt_pk_bf16_f32 v86, v210, v211
	v_cvt_pk_bf16_f32 v87, v212, v213
	v_lshlrev_b32_e32 v206, 16, v120
	v_and_b32_e32 v207, 0xffff0000, v120
	v_lshlrev_b32_e32 v208, 16, v121
	v_and_b32_e32 v209, 0xffff0000, v121
	v_lshlrev_b32_e32 v210, 16, v88
	v_and_b32_e32 v211, 0xffff0000, v88
	v_lshlrev_b32_e32 v212, 16, v89
	v_and_b32_e32 v213, 0xffff0000, v89
	v_pk_fma_f32 v[210:211], v[46:47], v[206:207], v[210:211]
	v_pk_fma_f32 v[212:213], v[48:49], v[208:209], v[212:213]
	v_cvt_pk_bf16_f32 v88, v210, v211
	v_cvt_pk_bf16_f32 v89, v212, v213
	v_lshlrev_b32_e32 v206, 16, v122
	v_and_b32_e32 v207, 0xffff0000, v122
	v_lshlrev_b32_e32 v208, 16, v123
	v_and_b32_e32 v209, 0xffff0000, v123
	v_lshlrev_b32_e32 v210, 16, v90
	v_and_b32_e32 v211, 0xffff0000, v90
	v_lshlrev_b32_e32 v212, 16, v91
	v_and_b32_e32 v213, 0xffff0000, v91
	v_pk_fma_f32 v[210:211], v[50:51], v[206:207], v[210:211]
	v_pk_fma_f32 v[212:213], v[52:53], v[208:209], v[212:213]
	v_cvt_pk_bf16_f32 v90, v210, v211
	v_cvt_pk_bf16_f32 v91, v212, v213
	v_lshlrev_b32_e32 v206, 16, v124
	v_and_b32_e32 v207, 0xffff0000, v124
	v_lshlrev_b32_e32 v208, 16, v125
	v_and_b32_e32 v209, 0xffff0000, v125
	v_lshlrev_b32_e32 v210, 16, v92
	v_and_b32_e32 v211, 0xffff0000, v92
	v_lshlrev_b32_e32 v212, 16, v93
	v_and_b32_e32 v213, 0xffff0000, v93
	v_pk_fma_f32 v[210:211], v[54:55], v[206:207], v[210:211]
	v_pk_fma_f32 v[212:213], v[56:57], v[208:209], v[212:213]
	v_cvt_pk_bf16_f32 v92, v210, v211
	v_cvt_pk_bf16_f32 v93, v212, v213
	v_lshlrev_b32_e32 v206, 16, v126
	v_and_b32_e32 v207, 0xffff0000, v126
	v_lshlrev_b32_e32 v208, 16, v127
	v_and_b32_e32 v209, 0xffff0000, v127
	v_lshlrev_b32_e32 v210, 16, v94
	v_and_b32_e32 v211, 0xffff0000, v94
	v_lshlrev_b32_e32 v212, 16, v95
	v_and_b32_e32 v213, 0xffff0000, v95
	v_pk_fma_f32 v[210:211], v[58:59], v[206:207], v[210:211]
	v_pk_fma_f32 v[212:213], v[60:61], v[208:209], v[212:213]
	v_cvt_pk_bf16_f32 v94, v210, v211
	v_cvt_pk_bf16_f32 v95, v212, v213
	v_lshlrev_b32_e32 v206, 16, v128
	v_and_b32_e32 v207, 0xffff0000, v128
	v_lshlrev_b32_e32 v208, 16, v129
	v_and_b32_e32 v209, 0xffff0000, v129
	v_lshlrev_b32_e32 v210, 16, v96
	v_and_b32_e32 v211, 0xffff0000, v96
	v_lshlrev_b32_e32 v212, 16, v97
	v_and_b32_e32 v213, 0xffff0000, v97
	v_pk_fma_f32 v[210:211], v[62:63], v[206:207], v[210:211]
	v_pk_fma_f32 v[212:213], v[64:65], v[208:209], v[212:213]
	v_cvt_pk_bf16_f32 v96, v210, v211
	v_cvt_pk_bf16_f32 v97, v212, v213
	s_mov_b64 s[80:81], s[76:77]
	v_mov_b32_e32 v206, v66
	v_mov_b32_e32 v207, v67
	v_mov_b32_e32 v208, v68
	v_mov_b32_e32 v209, v69
	s_nop 1
	v_permlane16_swap_b32 v206, v208
	s_nop 1
	s_nop 1
	v_permlane16_swap_b32 v207, v209
	s_nop 1
	global_store_dwordx4 v205, v[206:209], s[80:81] offset:0
	s_nop 1
	v_mov_b32_e32 v206, v70
	v_mov_b32_e32 v207, v71
	v_mov_b32_e32 v208, v72
	v_mov_b32_e32 v209, v73
	s_nop 1
	v_permlane16_swap_b32 v206, v208
	s_nop 1
	s_nop 1
	v_permlane16_swap_b32 v207, v209
	s_nop 1
	global_store_dwordx4 v205, v[206:209], s[80:81] offset:64
	s_nop 1
	s_add_u32 s80, s80, 0x8000
	s_addc_u32 s81, s81, 0
	v_mov_b32_e32 v206, v74
	v_mov_b32_e32 v207, v75
	v_mov_b32_e32 v208, v76
	v_mov_b32_e32 v209, v77
	s_nop 1
	v_permlane16_swap_b32 v206, v208
	s_nop 1
	s_nop 1
	v_permlane16_swap_b32 v207, v209
	s_nop 1
	global_store_dwordx4 v205, v[206:209], s[80:81] offset:0
	s_nop 1
	v_mov_b32_e32 v206, v78
	v_mov_b32_e32 v207, v79
	v_mov_b32_e32 v208, v80
	v_mov_b32_e32 v209, v81
	s_nop 1
	v_permlane16_swap_b32 v206, v208
	s_nop 1
	s_nop 1
	v_permlane16_swap_b32 v207, v209
	s_nop 1
	global_store_dwordx4 v205, v[206:209], s[80:81] offset:64
	s_nop 1
	s_add_u32 s80, s80, 0x8000
	s_addc_u32 s81, s81, 0
	v_mov_b32_e32 v206, v82
	v_mov_b32_e32 v207, v83
	v_mov_b32_e32 v208, v84
	v_mov_b32_e32 v209, v85
	s_nop 1
	v_permlane16_swap_b32 v206, v208
	s_nop 1
	s_nop 1
	v_permlane16_swap_b32 v207, v209
	s_nop 1
	global_store_dwordx4 v205, v[206:209], s[80:81] offset:0
	s_nop 1
	v_mov_b32_e32 v206, v86
	v_mov_b32_e32 v207, v87
	v_mov_b32_e32 v208, v88
	v_mov_b32_e32 v209, v89
	s_nop 1
	v_permlane16_swap_b32 v206, v208
	s_nop 1
	s_nop 1
	v_permlane16_swap_b32 v207, v209
	s_nop 1
	global_store_dwordx4 v205, v[206:209], s[80:81] offset:64
	s_nop 1
	s_add_u32 s80, s80, 0x8000
	s_addc_u32 s81, s81, 0
	v_mov_b32_e32 v206, v90
	v_mov_b32_e32 v207, v91
	v_mov_b32_e32 v208, v92
	v_mov_b32_e32 v209, v93
	s_nop 1
	v_permlane16_swap_b32 v206, v208
	s_nop 1
	s_nop 1
	v_permlane16_swap_b32 v207, v209
	s_nop 1
	global_store_dwordx4 v205, v[206:209], s[80:81] offset:0
	s_nop 1
	v_mov_b32_e32 v206, v94
	v_mov_b32_e32 v207, v95
	v_mov_b32_e32 v208, v96
	v_mov_b32_e32 v209, v97
	s_nop 1
	v_permlane16_swap_b32 v206, v208
	s_nop 1
	s_nop 1
	v_permlane16_swap_b32 v207, v209
	s_nop 1
	global_store_dwordx4 v205, v[206:209], s[80:81] offset:64
	s_nop 1
	s_add_i32 s5, s5, s4
	s_cmp_lt_i32 s5, s6
	s_cbranch_scc1 .Lph6_tile
	s_branch .LBB0_283

; #define LAS __attribute__((address_space(3)))
; __global__ void __launch_bounds__(512, 2) fwd_kernel(Args a) {
;     extern __shared__ __attribute__((aligned(16))) unsigned char lds_raw[];
;     LAS unsigned char* lds = (LAS unsigned char*)lds_raw;
;     cg::grid_group grid = cg::this_grid();
;     ...
;     const int s_lo = a.lo, s_hi = a.hi;
;     const int wv = __builtin_amdgcn_readfirstlane((int)threadIdx.x >> 6);
;     volatile LAS unsigned* bst = (volatile LAS unsigned*)(lds + 131072 + 1024);
	.amdhsa_kernel _Z10fwd_kernel4Args
		.amdhsa_group_segment_fixed_size 2048
		.amdhsa_private_segment_fixed_size 0
		.amdhsa_kernarg_size 480
		.amdhsa_user_sgpr_count 2
		.amdhsa_user_sgpr_dispatch_ptr 0
		.amdhsa_user_sgpr_queue_ptr 0
		.amdhsa_user_sgpr_kernarg_segment_ptr 1
		.amdhsa_user_sgpr_dispatch_id 0
		.amdhsa_user_sgpr_kernarg_preload_length 0
		.amdhsa_user_sgpr_kernarg_preload_offset 0
		.amdhsa_user_sgpr_private_segment_size 0
		.amdhsa_uses_dynamic_stack 0
		.amdhsa_enable_private_segment 0
		.amdhsa_system_sgpr_workgroup_id_x 1
		.amdhsa_system_sgpr_workgroup_id_y 0
		.amdhsa_system_sgpr_workgroup_id_z 0
		.amdhsa_system_sgpr_workgroup_info 0
		.amdhsa_system_vgpr_workitem_id 2
		.amdhsa_next_free_vgpr 256
		.amdhsa_next_free_sgpr 100
		.amdhsa_accum_offset 256
		.amdhsa_reserve_vcc 1
		.amdhsa_float_round_mode_32 0
		.amdhsa_float_round_mode_16_64 0
		.amdhsa_float_denorm_mode_32 3
		.amdhsa_float_denorm_mode_16_64 3
		.amdhsa_dx10_clamp 1
		.amdhsa_ieee_mode 1
		.amdhsa_fp16_overflow 0
		.amdhsa_tg_split 0
		.amdhsa_exception_fp_ieee_invalid_op 0
		.amdhsa_exception_fp_denorm_src 0
		.amdhsa_exception_fp_ieee_div_zero 0
		.amdhsa_exception_fp_ieee_overflow 0
		.amdhsa_exception_fp_ieee_underflow 0
		.amdhsa_exception_fp_ieee_inexact 0
		.amdhsa_exception_int_div_zero 0
	.end_amdhsa_kernel

; #define LAS __attribute__((address_space(3)))
; __global__ void __launch_bounds__(512, 2) fwd_kernel(Args a) {
;     extern __shared__ __attribute__((aligned(16))) unsigned char lds_raw[];
;     LAS unsigned char* lds = (LAS unsigned char*)lds_raw;
;     cg::grid_group grid = cg::this_grid();
;     ...
;     const int s_lo = a.lo, s_hi = a.hi;
;     const int wv = __builtin_amdgcn_readfirstlane((int)threadIdx.x >> 6);
;     volatile LAS unsigned* bst = (volatile LAS unsigned*)(lds + 131072 + 1024);
amdhsa.kernels:
  - .agpr_count:     0
    .args:
      - .offset:         0
        .size:           224
        .value_kind:     by_value
      - .offset:         224
        .size:           4
        .value_kind:     hidden_block_count_x
      - .offset:         228
        .size:           4
        .value_kind:     hidden_block_count_y
      - .offset:         232
        .size:           4
        .value_kind:     hidden_block_count_z
      - .offset:         236
        .size:           2
        .value_kind:     hidden_group_size_x
      - .offset:         238
        .size:           2
        .value_kind:     hidden_group_size_y
      - .offset:         240
        .size:           2
        .value_kind:     hidden_group_size_z
      - .offset:         242
        .size:           2
        .value_kind:     hidden_remainder_x
      - .offset:         244
        .size:           2
        .value_kind:     hidden_remainder_y
      - .offset:         246
        .size:           2
        .value_kind:     hidden_remainder_z
      - .offset:         264
        .size:           8
        .value_kind:     hidden_global_offset_x
      - .offset:         272
        .size:           8
        .value_kind:     hidden_global_offset_y
      - .offset:         280
        .size:           8
        .value_kind:     hidden_global_offset_z
      - .offset:         288
        .size:           2
        .value_kind:     hidden_grid_dims
      - .offset:         312
        .size:           8
        .value_kind:     hidden_multigrid_sync_arg
      - .offset:         344
        .size:           4
        .value_kind:     hidden_dynamic_lds_size
    .group_segment_fixed_size: 2048
    .kernarg_segment_align: 8
    .kernarg_segment_size: 480
    .language:       OpenCL C
    .language_version:
      - 2
      - 0
    .max_flat_workgroup_size: 512
    .name:           _Z10fwd_kernel4Args
    .private_segment_fixed_size: 0
    .sgpr_count:     106
    .sgpr_spill_count: 26
    .symbol:         _Z10fwd_kernel4Args.kd
    .uniform_work_group_size: 1
    .uses_dynamic_stack: false
    .vgpr_count:     256
    .vgpr_spill_count: 0
    .wavefront_size: 64
